# up-proj epilogue FMA pairing, second pass (merges in either direction, applied one at a time)
# speedup vs baseline: 1.0440x; 1.0008x over previous
.LBB0_563:
	s_or_b64 exec, exec, s[48:49]
	s_waitcnt lgkmcnt(0)
	s_barrier
	ds_read_b128 v[150:153], v223 offset:512
	ds_read_b128 v[154:157], v223 offset:1536
	ds_read_b128 v[162:165], v223 offset:2560
	ds_read_b128 v[138:141], v223 offset:3584
	v_mov_b32_e32 v158, 0
	v_mov_b32_e32 v159, 0
	v_mov_b32_e32 v160, 0
	v_mov_b32_e32 v161, 0
	s_and_saveexec_b64 s[48:49], s[30:31]
	v_add_u32_e32 v1, s91, v215
	ds_read_b128 v[158:161], v1 offset:512
	s_or_b64 exec, exec, s[48:49]
	v_lshl_add_u32 v1, s28, 1, v173
	v_mad_i64_i32 v[206:207], s[48:49], v1, s76, 0
	v_fmamk_f32 v1, v149, 0x3a800000, v222
	v_rsq_f32_e32 v196, v1
	v_fmamk_f32 v1, v146, 0x3a800000, v222
	v_rsq_f32_e32 v198, v1
	s_waitcnt lgkmcnt(0)
	v_fma_f32 v146, v166, v162, v138
	s_nop 4
	v_fmac_f32_dpp v146, v166, v154 row_shr:1 row_mask:0xf bank_mask:0xf
	v_fmamk_f32 v147, v148, 0x3a800000, v222
	v_fmac_f32_dpp v146, v166, v150 row_shr:2 row_mask:0xf bank_mask:0xf
	v_rsq_f32_e32 v194, v147
	v_pk_fma_f32 v[78:79], v[78:79], v[198:199], v[122:123] op_sel_hi:[1,0,1]
	v_fma_f32 v147, v167, v163, v139
	v_fmac_f32_dpp v146, v78, v154 row_shl:15 row_mask:0xf bank_mask:0xf
	v_pk_fma_f32 v[148:149], v[168:169], v[164:165], v[140:141]
	v_fmac_f32_dpp v146, v78, v150 row_shl:14 row_mask:0xf bank_mask:0xf
	v_fmac_f32_dpp v147, v167, v155 row_shr:1 row_mask:0xf bank_mask:0xf
	v_pk_fma_f32 v[80:81], v[80:81], v[198:199], v[124:125] op_sel_hi:[1,0,1]
	v_fmac_f32_dpp v147, v167, v151 row_shr:2 row_mask:0xf bank_mask:0xf
	s_nop 0
	v_fmac_f32_dpp v147, v79, v155 row_shl:15 row_mask:0xf bank_mask:0xf
	v_pk_fma_f32 v[224:225], v[130:131], v[196:197], v[122:123] op_sel_hi:[1,0,1]
	v_fmac_f32_dpp v147, v79, v151 row_shl:14 row_mask:0xf bank_mask:0xf
	v_fmac_f32_dpp v148, v168, v156 row_shr:1 row_mask:0xf bank_mask:0xf
	v_pk_fma_f32 v[130:131], v[78:79], v[162:163], v[138:139]
	v_fmac_f32_dpp v148, v168, v152 row_shr:2 row_mask:0xf bank_mask:0xf
	s_nop 0
	v_fmac_f32_dpp v148, v80, v156 row_shl:15 row_mask:0xf bank_mask:0xf
	v_pk_fma_f32 v[208:209], v[132:133], v[196:197], v[124:125] op_sel_hi:[1,0,1]
	v_fmac_f32_dpp v148, v80, v152 row_shl:14 row_mask:0xf bank_mask:0xf
	v_fmac_f32_dpp v149, v169, v157 row_shr:1 row_mask:0xf bank_mask:0xf
	v_pk_fma_f32 v[132:133], v[80:81], v[164:165], v[140:141]
	v_fmac_f32_dpp v149, v169, v153 row_shr:2 row_mask:0xf bank_mask:0xf
	s_nop 0
	v_fmac_f32_dpp v149, v81, v157 row_shl:15 row_mask:0xf bank_mask:0xf
	v_pk_fma_f32 v[134:135], v[134:135], v[194:195], v[122:123] op_sel_hi:[1,0,1]
	v_fmac_f32_dpp v149, v81, v153 row_shl:14 row_mask:0xf bank_mask:0xf
	v_pk_fma_f32 v[136:137], v[136:137], v[194:195], v[124:125] op_sel_hi:[1,0,1]
	v_fmac_f32_dpp v130, v78, v154 row_shr:1 row_mask:0xf bank_mask:0xf
	s_lshl_b32 s46, s46, 7
	v_fmac_f32_dpp v130, v78, v150 row_shr:2 row_mask:0xf bank_mask:0xf
	v_fma_f32 v78, v224, v162, v138
	v_fmac_f32_dpp v130, v224, v154 row_shl:15 row_mask:0xf bank_mask:0xf
	s_nop 0
	v_fmac_f32_dpp v130, v224, v150 row_shl:14 row_mask:0xf bank_mask:0xf
	v_fmac_f32_dpp v131, v79, v155 row_shr:1 row_mask:0xf bank_mask:0xf
	v_or_b32_e32 v200, s46, v184
	v_fmac_f32_dpp v131, v79, v151 row_shr:2 row_mask:0xf bank_mask:0xf
	v_fma_f32 v79, v225, v163, v139
	v_fmac_f32_dpp v131, v225, v155 row_shl:15 row_mask:0xf bank_mask:0xf
	v_pk_fma_f32 v[138:139], v[134:135], v[162:163], v[138:139]
	v_fmac_f32_dpp v131, v225, v151 row_shl:14 row_mask:0xf bank_mask:0xf
	v_fmac_f32_dpp v132, v80, v156 row_shr:1 row_mask:0xf bank_mask:0xf
	v_ashrrev_i32_e32 v201, 31, v200
	v_fmac_f32_dpp v132, v80, v152 row_shr:2 row_mask:0xf bank_mask:0xf
	v_fma_f32 v80, v208, v164, v140
	v_fmac_f32_dpp v132, v208, v156 row_shl:15 row_mask:0xf bank_mask:0xf
	s_nop 0
	v_fmac_f32_dpp v132, v208, v152 row_shl:14 row_mask:0xf bank_mask:0xf
	v_fmac_f32_dpp v133, v81, v157 row_shr:1 row_mask:0xf bank_mask:0xf
	v_lshl_add_u64 v[168:169], s[24:25], 0, v[206:207]
	v_fmac_f32_dpp v133, v81, v153 row_shr:2 row_mask:0xf bank_mask:0xf
	v_fma_f32 v81, v209, v165, v141
	v_fmac_f32_dpp v133, v209, v157 row_shl:15 row_mask:0xf bank_mask:0xf
	v_pk_fma_f32 v[140:141], v[136:137], v[164:165], v[140:141]
	v_fmac_f32_dpp v133, v209, v153 row_shl:14 row_mask:0xf bank_mask:0xf
	v_lshl_add_u64 v[166:167], v[200:201], 2, v[168:169]
	v_fmac_f32_dpp v78, v224, v154 row_shr:1 row_mask:0xf bank_mask:0xf
	s_nop 0
	v_fmac_f32_dpp v78, v224, v150 row_shr:2 row_mask:0xf bank_mask:0xf
	s_nop 0
	v_fmac_f32_dpp v78, v134, v154 row_shl:15 row_mask:0xf bank_mask:0xf
	s_nop 0
	v_fmac_f32_dpp v78, v134, v150 row_shl:14 row_mask:0xf bank_mask:0xf
	v_fmac_f32_dpp v79, v225, v155 row_shr:1 row_mask:0xf bank_mask:0xf
	s_nop 0
	v_fmac_f32_dpp v79, v225, v151 row_shr:2 row_mask:0xf bank_mask:0xf
	s_nop 0
	v_fmac_f32_dpp v79, v135, v155 row_shl:15 row_mask:0xf bank_mask:0xf
	s_nop 0
	v_fmac_f32_dpp v79, v135, v151 row_shl:14 row_mask:0xf bank_mask:0xf
	v_fmac_f32_dpp v80, v208, v156 row_shr:1 row_mask:0xf bank_mask:0xf
	s_nop 0
	v_fmac_f32_dpp v80, v208, v152 row_shr:2 row_mask:0xf bank_mask:0xf
	s_nop 0
	v_fmac_f32_dpp v80, v136, v156 row_shl:15 row_mask:0xf bank_mask:0xf
	s_nop 0
	v_fmac_f32_dpp v80, v136, v152 row_shl:14 row_mask:0xf bank_mask:0xf
	v_fmac_f32_dpp v81, v209, v157 row_shr:1 row_mask:0xf bank_mask:0xf
	s_nop 0
	v_fmac_f32_dpp v81, v209, v153 row_shr:2 row_mask:0xf bank_mask:0xf
	s_nop 0
	v_fmac_f32_dpp v81, v137, v157 row_shl:15 row_mask:0xf bank_mask:0xf
	s_nop 0
	v_fmac_f32_dpp v81, v137, v153 row_shl:14 row_mask:0xf bank_mask:0xf
	s_nop 0
	v_fmac_f32_dpp v138, v134, v154 row_shr:1 row_mask:0xf bank_mask:0xf
	s_nop 0
	v_fmac_f32_dpp v138, v134, v150 row_shr:2 row_mask:0xf bank_mask:0xf
	s_nop 0
	v_fmac_f32_dpp v138, v158, v154 row_shl:15 row_mask:0xf bank_mask:0xf
	s_nop 0
	v_fmac_f32_dpp v138, v158, v150 row_shl:14 row_mask:0xf bank_mask:0xf
	v_fmac_f32_dpp v139, v135, v155 row_shr:1 row_mask:0xf bank_mask:0xf
	s_nop 0
	v_fmac_f32_dpp v139, v135, v151 row_shr:2 row_mask:0xf bank_mask:0xf
	s_nop 0
	v_fmac_f32_dpp v139, v159, v155 row_shl:15 row_mask:0xf bank_mask:0xf
	s_nop 0
	v_fmac_f32_dpp v139, v159, v151 row_shl:14 row_mask:0xf bank_mask:0xf
	v_fmac_f32_dpp v140, v136, v156 row_shr:1 row_mask:0xf bank_mask:0xf
	s_nop 0
	v_fmac_f32_dpp v140, v136, v152 row_shr:2 row_mask:0xf bank_mask:0xf
	s_nop 0
	v_fmac_f32_dpp v140, v160, v156 row_shl:15 row_mask:0xf bank_mask:0xf
	s_nop 0
	v_fmac_f32_dpp v140, v160, v152 row_shl:14 row_mask:0xf bank_mask:0xf
	v_fmac_f32_dpp v141, v137, v157 row_shr:1 row_mask:0xf bank_mask:0xf
	s_nop 0
	v_fmac_f32_dpp v141, v137, v153 row_shr:2 row_mask:0xf bank_mask:0xf
	s_nop 0
	v_fmac_f32_dpp v141, v161, v157 row_shl:15 row_mask:0xf bank_mask:0xf
	s_nop 0
	v_fmac_f32_dpp v141, v161, v153 row_shl:14 row_mask:0xf bank_mask:0xf
	s_and_saveexec_b64 s[48:49], s[34:35]
	s_cbranch_execz .LBB0_567
	v_add_co_u32_e32 v134, vcc, 0x2000, v166
	s_nop 1
	v_addc_co_u32_e32 v135, vcc, 0, v167, vcc
	global_store_dwordx4 v[134:135], v[138:141], off offset:3072

.LBB0_571:
	s_or_b64 exec, exec, s[48:49]
	v_mul_f32_e32 v1, 0xbfb8aa3b, v134
	v_exp_f32_e32 v1, v1
	v_mul_f32_e32 v78, 0xbfb8aa3b, v135
	v_mul_f32_e32 v79, 0xbfb8aa3b, v136
	v_exp_f32_e32 v80, v78
	v_add_f32_e32 v1, 1.0, v1
	v_rcp_f32_e32 v78, v1
	v_exp_f32_e32 v1, v79
	v_mul_f32_e32 v79, 0xbfb8aa3b, v137
	v_exp_f32_e32 v79, v79
	v_add_f32_e32 v130, 1.0, v80
	v_add_f32_e32 v1, 1.0, v1
	v_rcp_f32_e32 v80, v1
	v_add_f32_e32 v1, 1.0, v79
	v_rcp_f32_e32 v81, v1
	v_rcp_f32_e32 v79, v130
	v_pk_mul_f32 v[130:131], v[140:141], v[136:137]
	v_pk_mul_f32 v[132:133], v[138:139], v[134:135]
	v_pk_mul_f32 v[80:81], v[130:131], v[80:81]
	v_pk_mul_f32 v[78:79], v[132:133], v[78:79]
	v_mov_b32_e32 v134, 0
	ds_read_b128 v[142:145], v223 offset:512
	ds_read_b128 v[146:149], v223 offset:1536
	ds_read_b128 v[154:157], v223 offset:2560
	ds_read_b128 v[130:133], v223 offset:3584
	v_mov_b32_e32 v150, 0
	v_mov_b32_e32 v151, 0
	v_mov_b32_e32 v152, 0
	v_mov_b32_e32 v153, 0
	s_and_saveexec_b64 s[48:49], s[0:1]
	v_add_u32_e32 v1, s91, v216
	ds_read_b128 v[150:153], v1 offset:512
	s_or_b64 exec, exec, s[48:49]
	v_fmamk_f32 v135, v202, 0x3a800000, v222
	v_rsq_f32_e32 v160, v135
	s_waitcnt lgkmcnt(0)
	v_pk_fma_f32 v[138:139], v[126:127], v[154:155], v[130:131]
	s_nop 4
	v_fmac_f32_dpp v138, v126, v146 row_shr:1 row_mask:0xf bank_mask:0xf
	v_pk_fma_f32 v[102:103], v[102:103], v[160:161], v[122:123] op_sel_hi:[1,0,1]
	v_fmac_f32_dpp v138, v126, v142 row_shr:2 row_mask:0xf bank_mask:0xf
	s_nop 0
	v_fmac_f32_dpp v138, v102, v146 row_shl:15 row_mask:0xf bank_mask:0xf
	v_pk_fma_f32 v[140:141], v[128:129], v[156:157], v[132:133]
	v_fmac_f32_dpp v138, v102, v142 row_shl:14 row_mask:0xf bank_mask:0xf
	v_fmac_f32_dpp v139, v127, v147 row_shr:1 row_mask:0xf bank_mask:0xf
	v_fmamk_f32 v1, v204, 0x3a800000, v222
	v_fmac_f32_dpp v139, v127, v143 row_shr:2 row_mask:0xf bank_mask:0xf
	v_rsq_f32_e32 v158, v1
	v_fmac_f32_dpp v139, v103, v147 row_shl:15 row_mask:0xf bank_mask:0xf
	v_fmamk_f32 v1, v205, 0x3a800000, v222
	v_fmac_f32_dpp v139, v103, v143 row_shl:14 row_mask:0xf bank_mask:0xf
	v_fmac_f32_dpp v140, v128, v148 row_shr:1 row_mask:0xf bank_mask:0xf
	v_rsq_f32_e32 v162, v1
	v_fmac_f32_dpp v140, v128, v144 row_shr:2 row_mask:0xf bank_mask:0xf
	v_pk_fma_f32 v[104:105], v[104:105], v[160:161], v[124:125] op_sel_hi:[1,0,1]
	s_nop 0
	v_fmac_f32_dpp v140, v104, v148 row_shl:15 row_mask:0xf bank_mask:0xf
	v_pk_fma_f32 v[164:165], v[106:107], v[162:163], v[122:123] op_sel_hi:[1,0,1]
	v_fmac_f32_dpp v140, v104, v144 row_shl:14 row_mask:0xf bank_mask:0xf
	v_fmac_f32_dpp v141, v129, v149 row_shr:1 row_mask:0xf bank_mask:0xf
	v_pk_fma_f32 v[106:107], v[102:103], v[154:155], v[130:131]
	v_fmac_f32_dpp v141, v129, v145 row_shr:2 row_mask:0xf bank_mask:0xf
	s_nop 0
	v_fmac_f32_dpp v141, v105, v149 row_shl:15 row_mask:0xf bank_mask:0xf
	v_pk_fma_f32 v[136:137], v[108:109], v[162:163], v[124:125] op_sel_hi:[1,0,1]
	v_fmac_f32_dpp v141, v105, v145 row_shl:14 row_mask:0xf bank_mask:0xf
	v_pk_fma_f32 v[108:109], v[104:105], v[156:157], v[132:133]
	v_fmac_f32_dpp v106, v102, v146 row_shr:1 row_mask:0xf bank_mask:0xf
	s_nop 0
	v_fmac_f32_dpp v106, v102, v142 row_shr:2 row_mask:0xf bank_mask:0xf
	s_nop 0
	v_fmac_f32_dpp v106, v164, v146 row_shl:15 row_mask:0xf bank_mask:0xf
	v_pk_fma_f32 v[110:111], v[110:111], v[158:159], v[122:123] op_sel_hi:[1,0,1]
	v_fmac_f32_dpp v106, v164, v142 row_shl:14 row_mask:0xf bank_mask:0xf
	v_fmac_f32_dpp v107, v103, v147 row_shr:1 row_mask:0xf bank_mask:0xf
	v_pk_fma_f32 v[112:113], v[112:113], v[158:159], v[124:125] op_sel_hi:[1,0,1]
	v_fmac_f32_dpp v107, v103, v143 row_shr:2 row_mask:0xf bank_mask:0xf
	v_pk_fma_f32 v[102:103], v[164:165], v[154:155], v[130:131]
	v_fmac_f32_dpp v107, v165, v147 row_shl:15 row_mask:0xf bank_mask:0xf
	v_pk_fma_f32 v[130:131], v[110:111], v[154:155], v[130:131]
	v_fmac_f32_dpp v107, v165, v143 row_shl:14 row_mask:0xf bank_mask:0xf
	v_fmac_f32_dpp v108, v104, v148 row_shr:1 row_mask:0xf bank_mask:0xf
	s_nop 0
	v_fmac_f32_dpp v108, v104, v144 row_shr:2 row_mask:0xf bank_mask:0xf
	v_fma_f32 v104, v136, v156, v132
	v_fmac_f32_dpp v108, v136, v148 row_shl:15 row_mask:0xf bank_mask:0xf
	s_nop 0
	v_fmac_f32_dpp v108, v136, v144 row_shl:14 row_mask:0xf bank_mask:0xf
	v_fmac_f32_dpp v109, v105, v149 row_shr:1 row_mask:0xf bank_mask:0xf
	v_mov_b32_e32 v135, 0
	v_fmac_f32_dpp v109, v105, v145 row_shr:2 row_mask:0xf bank_mask:0xf
	v_fma_f32 v105, v137, v157, v133
	v_fmac_f32_dpp v109, v137, v149 row_shl:15 row_mask:0xf bank_mask:0xf
	v_pk_fma_f32 v[132:133], v[112:113], v[156:157], v[132:133]
	v_fmac_f32_dpp v109, v137, v145 row_shl:14 row_mask:0xf bank_mask:0xf
	s_nop 0
	v_fmac_f32_dpp v102, v164, v146 row_shr:1 row_mask:0xf bank_mask:0xf
	s_nop 0
	v_fmac_f32_dpp v102, v164, v142 row_shr:2 row_mask:0xf bank_mask:0xf
	s_nop 0
	v_fmac_f32_dpp v102, v110, v146 row_shl:15 row_mask:0xf bank_mask:0xf
	s_nop 0
	v_fmac_f32_dpp v102, v110, v142 row_shl:14 row_mask:0xf bank_mask:0xf
	v_fmac_f32_dpp v103, v165, v147 row_shr:1 row_mask:0xf bank_mask:0xf
	s_nop 0
	v_fmac_f32_dpp v103, v165, v143 row_shr:2 row_mask:0xf bank_mask:0xf
	s_nop 0
	v_fmac_f32_dpp v103, v111, v147 row_shl:15 row_mask:0xf bank_mask:0xf
	s_nop 0
	v_fmac_f32_dpp v103, v111, v143 row_shl:14 row_mask:0xf bank_mask:0xf
	v_fmac_f32_dpp v104, v136, v148 row_shr:1 row_mask:0xf bank_mask:0xf
	s_nop 0
	v_fmac_f32_dpp v104, v136, v144 row_shr:2 row_mask:0xf bank_mask:0xf
	v_mov_b32_e32 v136, 0
	v_fmac_f32_dpp v104, v112, v148 row_shl:15 row_mask:0xf bank_mask:0xf
	s_nop 0
	v_fmac_f32_dpp v104, v112, v144 row_shl:14 row_mask:0xf bank_mask:0xf
	v_fmac_f32_dpp v105, v137, v149 row_shr:1 row_mask:0xf bank_mask:0xf
	s_nop 0
	v_fmac_f32_dpp v105, v137, v145 row_shr:2 row_mask:0xf bank_mask:0xf
	v_mov_b32_e32 v137, 0
	v_fmac_f32_dpp v105, v113, v149 row_shl:15 row_mask:0xf bank_mask:0xf
	s_nop 0
	v_fmac_f32_dpp v105, v113, v145 row_shl:14 row_mask:0xf bank_mask:0xf
	s_nop 0
	v_fmac_f32_dpp v130, v110, v146 row_shr:1 row_mask:0xf bank_mask:0xf
	s_nop 0
	v_fmac_f32_dpp v130, v110, v142 row_shr:2 row_mask:0xf bank_mask:0xf
	s_nop 0
	v_fmac_f32_dpp v130, v150, v146 row_shl:15 row_mask:0xf bank_mask:0xf
	s_nop 0
	v_fmac_f32_dpp v130, v150, v142 row_shl:14 row_mask:0xf bank_mask:0xf
	v_fmac_f32_dpp v131, v111, v147 row_shr:1 row_mask:0xf bank_mask:0xf
	s_nop 0
	v_fmac_f32_dpp v131, v111, v143 row_shr:2 row_mask:0xf bank_mask:0xf
	s_nop 0
	v_fmac_f32_dpp v131, v151, v147 row_shl:15 row_mask:0xf bank_mask:0xf
	s_nop 0
	v_fmac_f32_dpp v131, v151, v143 row_shl:14 row_mask:0xf bank_mask:0xf
	v_fmac_f32_dpp v132, v112, v148 row_shr:1 row_mask:0xf bank_mask:0xf
	s_nop 0
	v_fmac_f32_dpp v132, v112, v144 row_shr:2 row_mask:0xf bank_mask:0xf
	s_nop 0
	v_fmac_f32_dpp v132, v152, v148 row_shl:15 row_mask:0xf bank_mask:0xf
	s_nop 0
	v_fmac_f32_dpp v132, v152, v144 row_shl:14 row_mask:0xf bank_mask:0xf
	v_fmac_f32_dpp v133, v113, v149 row_shr:1 row_mask:0xf bank_mask:0xf
	s_nop 0
	v_fmac_f32_dpp v133, v113, v145 row_shr:2 row_mask:0xf bank_mask:0xf
	s_nop 0
	v_fmac_f32_dpp v133, v153, v149 row_shl:15 row_mask:0xf bank_mask:0xf
	s_nop 0
	v_fmac_f32_dpp v133, v153, v145 row_shl:14 row_mask:0xf bank_mask:0xf
	s_nop 0
	ds_read_b128 v[122:125], v223
	ds_read_b128 v[126:129], v223 offset:1024
	ds_read_b128 v[142:145], v223 offset:2048
	ds_read_b128 v[110:113], v223 offset:3072
	s_and_saveexec_b64 s[48:49], s[0:1]
	v_add_u32_e32 v1, 0, v216
	v_add_u32_e32 v1, 0x20000, v1
	ds_read_b128 v[134:137], v1
	s_or_b64 exec, exec, s[48:49]
	v_mov_b32_e32 v159, v158
	v_mov_b32_e32 v161, v160
	v_pk_fma_f32 v[148:149], v[94:95], v[158:159], v[118:119]
	v_mov_b32_e32 v94, v162
	v_mov_b32_e32 v95, v162
	v_pk_fma_f32 v[94:95], v[92:93], v[94:95], v[120:121]
	v_pk_fma_f32 v[92:93], v[86:87], v[160:161], v[118:119]
	s_waitcnt lgkmcnt(0)
	v_pk_fma_f32 v[86:87], v[114:115], v[142:143], v[110:111]
	s_nop 4
	v_fmac_f32_dpp v86, v114, v126 row_shr:1 row_mask:0xf bank_mask:0xf
	s_nop 0
	v_fmac_f32_dpp v86, v114, v122 row_shr:2 row_mask:0xf bank_mask:0xf
	v_mov_b32_e32 v163, v162
	v_fmac_f32_dpp v86, v92, v126 row_shl:15 row_mask:0xf bank_mask:0xf
	v_mov_b32_e32 v146, v158
	v_mov_b32_e32 v147, v158
	v_fmac_f32_dpp v86, v92, v122 row_shl:14 row_mask:0xf bank_mask:0xf
	v_fmac_f32_dpp v87, v115, v127 row_shr:1 row_mask:0xf bank_mask:0xf
	v_pk_fma_f32 v[146:147], v[96:97], v[146:147], v[120:121]
	v_pk_fma_f32 v[96:97], v[90:91], v[162:163], v[118:119]
	v_mov_b32_e32 v90, v160
	v_mov_b32_e32 v91, v160
	v_fmac_f32_dpp v87, v115, v123 row_shr:2 row_mask:0xf bank_mask:0xf
	v_pk_fma_f32 v[90:91], v[88:89], v[90:91], v[120:121]
	v_fmac_f32_dpp v87, v93, v127 row_shl:15 row_mask:0xf bank_mask:0xf
	v_pk_fma_f32 v[88:89], v[116:117], v[144:145], v[112:113]
	v_fmac_f32_dpp v87, v93, v123 row_shl:14 row_mask:0xf bank_mask:0xf
	v_fmac_f32_dpp v88, v116, v128 row_shr:1 row_mask:0xf bank_mask:0xf
	v_mul_f32_e32 v1, 0xbfb8aa3b, v86
	v_fmac_f32_dpp v88, v116, v124 row_shr:2 row_mask:0xf bank_mask:0xf
	v_exp_f32_e32 v1, v1
	v_fmac_f32_dpp v88, v90, v128 row_shl:15 row_mask:0xf bank_mask:0xf
	s_nop 0
	v_fmac_f32_dpp v88, v90, v124 row_shl:14 row_mask:0xf bank_mask:0xf
	v_fmac_f32_dpp v89, v117, v129 row_shr:1 row_mask:0xf bank_mask:0xf
	v_add_f32_e32 v1, 1.0, v1
	v_fmac_f32_dpp v89, v117, v125 row_shr:2 row_mask:0xf bank_mask:0xf
	v_mul_f32_e32 v115, 0xbfb8aa3b, v88
	v_fmac_f32_dpp v89, v91, v129 row_shl:15 row_mask:0xf bank_mask:0xf
	v_rcp_f32_e32 v114, v1
	v_fmac_f32_dpp v89, v91, v125 row_shl:14 row_mask:0xf bank_mask:0xf
	v_mul_f32_e32 v1, 0xbfb8aa3b, v87
	v_exp_f32_e32 v115, v115
	v_mul_f32_e32 v116, 0xbfb8aa3b, v89
	v_exp_f32_e32 v1, v1
	v_exp_f32_e32 v117, v116
	v_add_f32_e32 v115, 1.0, v115
	v_rcp_f32_e32 v116, v115
	v_add_f32_e32 v1, 1.0, v1
	v_add_f32_e32 v115, 1.0, v117
	v_rcp_f32_e32 v117, v115
	v_rcp_f32_e32 v115, v1
	v_pk_mul_f32 v[88:89], v[140:141], v[88:89]
	v_pk_mul_f32 v[86:87], v[138:139], v[86:87]
	v_pk_mul_f32 v[88:89], v[88:89], v[116:117]
	v_pk_mul_f32 v[86:87], v[86:87], v[114:115]
	v_pk_fma_f32 v[114:115], v[92:93], v[142:143], v[110:111]
	v_fmac_f32_dpp v114, v92, v126 row_shr:1 row_mask:0xf bank_mask:0xf
	s_nop 0
	v_fmac_f32_dpp v114, v92, v122 row_shr:2 row_mask:0xf bank_mask:0xf
	v_fma_f32 v92, v90, v144, v112
	v_fmac_f32_dpp v114, v96, v126 row_shl:15 row_mask:0xf bank_mask:0xf
	s_nop 0
	v_fmac_f32_dpp v114, v96, v122 row_shl:14 row_mask:0xf bank_mask:0xf
	v_fmac_f32_dpp v115, v93, v127 row_shr:1 row_mask:0xf bank_mask:0xf
	s_nop 0
	v_fmac_f32_dpp v115, v93, v123 row_shr:2 row_mask:0xf bank_mask:0xf
	v_mul_f32_e32 v1, 0xbfb8aa3b, v114
	v_fmac_f32_dpp v115, v97, v127 row_shl:15 row_mask:0xf bank_mask:0xf
	v_exp_f32_e32 v1, v1
	v_fmac_f32_dpp v115, v97, v123 row_shl:14 row_mask:0xf bank_mask:0xf
	v_fmac_f32_dpp v92, v90, v128 row_shr:1 row_mask:0xf bank_mask:0xf
	v_fma_f32 v93, v91, v145, v113
	v_fmac_f32_dpp v92, v90, v124 row_shr:2 row_mask:0xf bank_mask:0xf
	v_add_f32_e32 v1, 1.0, v1
	v_fmac_f32_dpp v92, v94, v128 row_shl:15 row_mask:0xf bank_mask:0xf
	v_rcp_f32_e32 v90, v1
	v_fmac_f32_dpp v92, v94, v124 row_shl:14 row_mask:0xf bank_mask:0xf
	v_fmac_f32_dpp v93, v91, v129 row_shr:1 row_mask:0xf bank_mask:0xf
	v_mul_f32_e32 v1, 0xbfb8aa3b, v115
	v_fmac_f32_dpp v93, v91, v125 row_shr:2 row_mask:0xf bank_mask:0xf
	v_mul_f32_e32 v91, 0xbfb8aa3b, v92
	v_fmac_f32_dpp v93, v95, v129 row_shl:15 row_mask:0xf bank_mask:0xf
	v_exp_f32_e32 v91, v91
	v_fmac_f32_dpp v93, v95, v125 row_shl:14 row_mask:0xf bank_mask:0xf
	v_exp_f32_e32 v1, v1
	v_mul_f32_e32 v116, 0xbfb8aa3b, v93
	v_exp_f32_e32 v117, v116
	v_add_f32_e32 v91, 1.0, v91
	v_add_f32_e32 v1, 1.0, v1
	v_rcp_f32_e32 v116, v91
	v_add_f32_e32 v91, 1.0, v117
	v_rcp_f32_e32 v117, v91
	v_rcp_f32_e32 v91, v1
	v_pk_mul_f32 v[92:93], v[108:109], v[92:93]
	v_pk_mul_f32 v[106:107], v[106:107], v[114:115]
	v_pk_mul_f32 v[92:93], v[92:93], v[116:117]
	v_pk_mul_f32 v[90:91], v[106:107], v[90:91]
	v_pk_fma_f32 v[106:107], v[96:97], v[142:143], v[110:111]
	v_fmac_f32_dpp v106, v96, v126 row_shr:1 row_mask:0xf bank_mask:0xf
	s_nop 0
	v_fmac_f32_dpp v106, v96, v122 row_shr:2 row_mask:0xf bank_mask:0xf
	v_fma_f32 v96, v94, v144, v112
	v_fmac_f32_dpp v106, v148, v126 row_shl:15 row_mask:0xf bank_mask:0xf
	s_nop 0
	v_fmac_f32_dpp v106, v148, v122 row_shl:14 row_mask:0xf bank_mask:0xf
	v_fmac_f32_dpp v107, v97, v127 row_shr:1 row_mask:0xf bank_mask:0xf
	s_nop 0
	v_fmac_f32_dpp v107, v97, v123 row_shr:2 row_mask:0xf bank_mask:0xf
	v_mul_f32_e32 v1, 0xbfb8aa3b, v106
	v_fmac_f32_dpp v107, v149, v127 row_shl:15 row_mask:0xf bank_mask:0xf
	v_exp_f32_e32 v1, v1
	v_fmac_f32_dpp v107, v149, v123 row_shl:14 row_mask:0xf bank_mask:0xf
	v_fmac_f32_dpp v96, v94, v128 row_shr:1 row_mask:0xf bank_mask:0xf
	v_fma_f32 v97, v95, v145, v113
	v_fmac_f32_dpp v96, v94, v124 row_shr:2 row_mask:0xf bank_mask:0xf
	v_add_f32_e32 v1, 1.0, v1
	v_fmac_f32_dpp v96, v146, v128 row_shl:15 row_mask:0xf bank_mask:0xf
	v_rcp_f32_e32 v94, v1
	v_fmac_f32_dpp v96, v146, v124 row_shl:14 row_mask:0xf bank_mask:0xf
	v_fmac_f32_dpp v97, v95, v129 row_shr:1 row_mask:0xf bank_mask:0xf
	v_mul_f32_e32 v1, 0xbfb8aa3b, v107
	v_fmac_f32_dpp v97, v95, v125 row_shr:2 row_mask:0xf bank_mask:0xf
	v_mul_f32_e32 v95, 0xbfb8aa3b, v96
	v_fmac_f32_dpp v97, v147, v129 row_shl:15 row_mask:0xf bank_mask:0xf
	v_exp_f32_e32 v95, v95
	v_fmac_f32_dpp v97, v147, v125 row_shl:14 row_mask:0xf bank_mask:0xf
	v_exp_f32_e32 v1, v1
	v_mul_f32_e32 v108, 0xbfb8aa3b, v97
	v_exp_f32_e32 v109, v108
	v_add_f32_e32 v95, 1.0, v95
	v_add_f32_e32 v1, 1.0, v1
	v_rcp_f32_e32 v108, v95
	v_add_f32_e32 v95, 1.0, v109
	v_rcp_f32_e32 v109, v95
	v_rcp_f32_e32 v95, v1
	v_pk_mul_f32 v[96:97], v[104:105], v[96:97]
	v_pk_mul_f32 v[102:103], v[102:103], v[106:107]
	v_pk_mul_f32 v[96:97], v[96:97], v[108:109]
	v_pk_mul_f32 v[94:95], v[102:103], v[94:95]
	v_pk_fma_f32 v[102:103], v[148:149], v[142:143], v[110:111]
	v_fmac_f32_dpp v102, v148, v126 row_shr:1 row_mask:0xf bank_mask:0xf
	s_nop 0
	v_fmac_f32_dpp v102, v148, v122 row_shr:2 row_mask:0xf bank_mask:0xf
	v_pk_fma_f32 v[112:113], v[146:147], v[144:145], v[112:113]
	v_fmac_f32_dpp v102, v134, v126 row_shl:15 row_mask:0xf bank_mask:0xf
	s_nop 0
	v_fmac_f32_dpp v102, v134, v122 row_shl:14 row_mask:0xf bank_mask:0xf
	v_fmac_f32_dpp v103, v149, v127 row_shr:1 row_mask:0xf bank_mask:0xf
	v_mov_b32_e32 v122, 0
	v_fmac_f32_dpp v103, v149, v123 row_shr:2 row_mask:0xf bank_mask:0xf
	v_mul_f32_e32 v1, 0xbfb8aa3b, v102
	v_fmac_f32_dpp v103, v135, v127 row_shl:15 row_mask:0xf bank_mask:0xf
	v_exp_f32_e32 v1, v1
	v_fmac_f32_dpp v103, v135, v123 row_shl:14 row_mask:0xf bank_mask:0xf
	v_fmac_f32_dpp v112, v146, v128 row_shr:1 row_mask:0xf bank_mask:0xf
	v_mov_b32_e32 v123, 0
	v_fmac_f32_dpp v112, v146, v124 row_shr:2 row_mask:0xf bank_mask:0xf
	v_add_f32_e32 v1, 1.0, v1
	v_fmac_f32_dpp v112, v136, v128 row_shl:15 row_mask:0xf bank_mask:0xf
	v_rcp_f32_e32 v106, v1
	v_fmac_f32_dpp v112, v136, v124 row_shl:14 row_mask:0xf bank_mask:0xf
	v_fmac_f32_dpp v113, v147, v129 row_shr:1 row_mask:0xf bank_mask:0xf
	v_mul_f32_e32 v1, 0xbfb8aa3b, v103
	v_fmac_f32_dpp v113, v147, v125 row_shr:2 row_mask:0xf bank_mask:0xf
	v_mul_f32_e32 v104, 0xbfb8aa3b, v112
	v_fmac_f32_dpp v113, v137, v129 row_shl:15 row_mask:0xf bank_mask:0xf
	v_exp_f32_e32 v1, v1
	v_fmac_f32_dpp v113, v137, v125 row_shl:14 row_mask:0xf bank_mask:0xf
	v_exp_f32_e32 v104, v104
	v_mul_f32_e32 v105, 0xbfb8aa3b, v113
	v_exp_f32_e32 v105, v105
	v_add_f32_e32 v1, 1.0, v1
	v_add_f32_e32 v104, 1.0, v104
	v_rcp_f32_e32 v104, v104
	v_add_f32_e32 v105, 1.0, v105
	v_rcp_f32_e32 v105, v105
	v_rcp_f32_e32 v107, v1
	v_pk_mul_f32 v[108:109], v[132:133], v[112:113]
	v_pk_mul_f32 v[102:103], v[130:131], v[102:103]
	v_pk_mul_f32 v[104:105], v[108:109], v[104:105]
	v_pk_mul_f32 v[102:103], v[102:103], v[106:107]
	v_mov_b32_e32 v124, 0
	ds_read_b128 v[114:117], v223 offset:528
	ds_read_b128 v[118:121], v223 offset:1552
	ds_read_b128 v[126:129], v223 offset:2576
	ds_read_b128 v[106:109], v223 offset:3600
	v_mov_b32_e32 v125, 0
	s_and_saveexec_b64 s[48:49], s[30:31]
	v_add_u32_e32 v1, s91, v217
	ds_read_b128 v[122:125], v1 offset:512
	s_or_b64 exec, exec, s[48:49]
	v_mov_b32_e32 v110, v194
	v_mov_b32_e32 v111, v194
	v_pk_fma_f32 v[76:77], v[76:77], v[110:111], v[56:57]
	v_mov_b32_e32 v110, v196
	v_mov_b32_e32 v111, v196
	v_pk_fma_f32 v[130:131], v[72:73], v[110:111], v[56:57]
	s_waitcnt lgkmcnt(0)
	v_pk_fma_f32 v[110:111], v[98:99], v[126:127], v[106:107]
	s_nop 4
	v_fmac_f32_dpp v110, v98, v118 row_shr:1 row_mask:0xf bank_mask:0xf
	v_pk_fma_f32 v[66:67], v[66:67], v[198:199], v[54:55]
	v_fmac_f32_dpp v110, v98, v114 row_shr:2 row_mask:0xf bank_mask:0xf
	s_nop 0
	v_fmac_f32_dpp v110, v66, v118 row_shl:15 row_mask:0xf bank_mask:0xf
	v_pk_fma_f32 v[112:113], v[100:101], v[128:129], v[108:109]
	v_fmac_f32_dpp v110, v66, v114 row_shl:14 row_mask:0xf bank_mask:0xf
	v_fmac_f32_dpp v111, v99, v119 row_shr:1 row_mask:0xf bank_mask:0xf
	v_pk_fma_f32 v[132:133], v[70:71], v[196:197], v[54:55]
	v_fmac_f32_dpp v111, v99, v115 row_shr:2 row_mask:0xf bank_mask:0xf
	v_mov_b32_e32 v70, v198
	v_fmac_f32_dpp v111, v67, v119 row_shl:15 row_mask:0xf bank_mask:0xf
	v_mov_b32_e32 v71, v198
	v_fmac_f32_dpp v111, v67, v115 row_shl:14 row_mask:0xf bank_mask:0xf
	v_fmac_f32_dpp v112, v100, v120 row_shr:1 row_mask:0xf bank_mask:0xf
	v_pk_fma_f32 v[68:69], v[68:69], v[70:71], v[56:57]
	v_fmac_f32_dpp v112, v100, v116 row_shr:2 row_mask:0xf bank_mask:0xf
	s_nop 0
	v_fmac_f32_dpp v112, v68, v120 row_shl:15 row_mask:0xf bank_mask:0xf
	v_pk_fma_f32 v[70:71], v[66:67], v[126:127], v[106:107]
	v_fmac_f32_dpp v112, v68, v116 row_shl:14 row_mask:0xf bank_mask:0xf
	v_fmac_f32_dpp v113, v101, v121 row_shr:1 row_mask:0xf bank_mask:0xf
	s_nop 0
	v_fmac_f32_dpp v113, v101, v117 row_shr:2 row_mask:0xf bank_mask:0xf
	v_pk_fma_f32 v[72:73], v[68:69], v[128:129], v[108:109]
	v_fmac_f32_dpp v113, v69, v121 row_shl:15 row_mask:0xf bank_mask:0xf
	s_nop 0
	v_fmac_f32_dpp v113, v69, v117 row_shl:14 row_mask:0xf bank_mask:0xf
	v_pk_fma_f32 v[74:75], v[74:75], v[194:195], v[54:55]
	v_fmac_f32_dpp v70, v66, v118 row_shr:1 row_mask:0xf bank_mask:0xf
	s_nop 0
	v_fmac_f32_dpp v70, v66, v114 row_shr:2 row_mask:0xf bank_mask:0xf
	v_fma_f32 v66, v132, v126, v106
	v_fmac_f32_dpp v70, v132, v118 row_shl:15 row_mask:0xf bank_mask:0xf
	s_nop 0
	v_fmac_f32_dpp v70, v132, v114 row_shl:14 row_mask:0xf bank_mask:0xf
	v_fmac_f32_dpp v71, v67, v119 row_shr:1 row_mask:0xf bank_mask:0xf
	s_nop 0
	v_fmac_f32_dpp v71, v67, v115 row_shr:2 row_mask:0xf bank_mask:0xf
	v_fma_f32 v67, v133, v127, v107
	v_fmac_f32_dpp v71, v133, v119 row_shl:15 row_mask:0xf bank_mask:0xf
	v_pk_fma_f32 v[106:107], v[74:75], v[126:127], v[106:107]
	v_fmac_f32_dpp v71, v133, v115 row_shl:14 row_mask:0xf bank_mask:0xf
	v_fmac_f32_dpp v72, v68, v120 row_shr:1 row_mask:0xf bank_mask:0xf
	s_nop 0
	v_fmac_f32_dpp v72, v68, v116 row_shr:2 row_mask:0xf bank_mask:0xf
	v_fma_f32 v68, v130, v128, v108
	v_fmac_f32_dpp v72, v130, v120 row_shl:15 row_mask:0xf bank_mask:0xf
	s_nop 0
	v_fmac_f32_dpp v72, v130, v116 row_shl:14 row_mask:0xf bank_mask:0xf
	v_fmac_f32_dpp v73, v69, v121 row_shr:1 row_mask:0xf bank_mask:0xf
	s_nop 0
	v_fmac_f32_dpp v73, v69, v117 row_shr:2 row_mask:0xf bank_mask:0xf
	v_fma_f32 v69, v131, v129, v109
	v_fmac_f32_dpp v73, v131, v121 row_shl:15 row_mask:0xf bank_mask:0xf
	v_pk_fma_f32 v[108:109], v[76:77], v[128:129], v[108:109]
	v_fmac_f32_dpp v73, v131, v117 row_shl:14 row_mask:0xf bank_mask:0xf
	s_nop 0
	v_fmac_f32_dpp v66, v132, v118 row_shr:1 row_mask:0xf bank_mask:0xf
	s_nop 0
	v_fmac_f32_dpp v66, v132, v114 row_shr:2 row_mask:0xf bank_mask:0xf
	s_nop 0
	v_fmac_f32_dpp v66, v74, v118 row_shl:15 row_mask:0xf bank_mask:0xf
	s_nop 0
	v_fmac_f32_dpp v66, v74, v114 row_shl:14 row_mask:0xf bank_mask:0xf
	v_fmac_f32_dpp v67, v133, v119 row_shr:1 row_mask:0xf bank_mask:0xf
	s_nop 0
	v_fmac_f32_dpp v67, v133, v115 row_shr:2 row_mask:0xf bank_mask:0xf
	s_nop 0
	v_fmac_f32_dpp v67, v75, v119 row_shl:15 row_mask:0xf bank_mask:0xf
	s_nop 0
	v_fmac_f32_dpp v67, v75, v115 row_shl:14 row_mask:0xf bank_mask:0xf
	v_fmac_f32_dpp v68, v130, v120 row_shr:1 row_mask:0xf bank_mask:0xf
	s_nop 0
	v_fmac_f32_dpp v68, v130, v116 row_shr:2 row_mask:0xf bank_mask:0xf
	s_nop 0
	v_fmac_f32_dpp v68, v76, v120 row_shl:15 row_mask:0xf bank_mask:0xf
	s_nop 0
	v_fmac_f32_dpp v68, v76, v116 row_shl:14 row_mask:0xf bank_mask:0xf
	v_fmac_f32_dpp v69, v131, v121 row_shr:1 row_mask:0xf bank_mask:0xf
	s_nop 0
	v_fmac_f32_dpp v69, v131, v117 row_shr:2 row_mask:0xf bank_mask:0xf
	s_nop 0
	v_fmac_f32_dpp v69, v77, v121 row_shl:15 row_mask:0xf bank_mask:0xf
	s_nop 0
	v_fmac_f32_dpp v69, v77, v117 row_shl:14 row_mask:0xf bank_mask:0xf
	s_nop 0
	v_fmac_f32_dpp v106, v74, v118 row_shr:1 row_mask:0xf bank_mask:0xf
	s_nop 0
	v_fmac_f32_dpp v106, v74, v114 row_shr:2 row_mask:0xf bank_mask:0xf
	s_nop 0
	v_fmac_f32_dpp v106, v122, v118 row_shl:15 row_mask:0xf bank_mask:0xf
	s_nop 0
	v_fmac_f32_dpp v106, v122, v114 row_shl:14 row_mask:0xf bank_mask:0xf
	v_fmac_f32_dpp v107, v75, v119 row_shr:1 row_mask:0xf bank_mask:0xf
	s_nop 0
	v_fmac_f32_dpp v107, v75, v115 row_shr:2 row_mask:0xf bank_mask:0xf
	s_nop 0
	v_fmac_f32_dpp v107, v123, v119 row_shl:15 row_mask:0xf bank_mask:0xf
	s_nop 0
	v_fmac_f32_dpp v107, v123, v115 row_shl:14 row_mask:0xf bank_mask:0xf
	v_fmac_f32_dpp v108, v76, v120 row_shr:1 row_mask:0xf bank_mask:0xf
	s_nop 0
	v_fmac_f32_dpp v108, v76, v116 row_shr:2 row_mask:0xf bank_mask:0xf
	s_nop 0
	v_fmac_f32_dpp v108, v124, v120 row_shl:15 row_mask:0xf bank_mask:0xf
	s_nop 0
	v_fmac_f32_dpp v108, v124, v116 row_shl:14 row_mask:0xf bank_mask:0xf
	v_fmac_f32_dpp v109, v77, v121 row_shr:1 row_mask:0xf bank_mask:0xf
	s_nop 0
	v_fmac_f32_dpp v109, v77, v117 row_shr:2 row_mask:0xf bank_mask:0xf
	s_nop 0
	v_fmac_f32_dpp v109, v125, v121 row_shl:15 row_mask:0xf bank_mask:0xf
	s_nop 0
	v_fmac_f32_dpp v109, v125, v117 row_shl:14 row_mask:0xf bank_mask:0xf
	s_and_saveexec_b64 s[48:49], s[34:35]
	s_cbranch_execz .LBB0_579
	v_or_b32_e32 v74, 4, v200
	v_ashrrev_i32_e32 v75, 31, v74
	v_lshl_add_u64 v[74:75], v[74:75], 2, v[168:169]
	v_add_co_u32_e32 v74, vcc, 0x2000, v74
	s_nop 1
	v_addc_co_u32_e32 v75, vcc, 0, v75, vcc
	global_store_dwordx4 v[74:75], v[106:109], off offset:3072

.LBB0_583:
	s_or_b64 exec, exec, s[48:49]
	v_mul_f32_e32 v1, 0xbfb8aa3b, v74
	v_exp_f32_e32 v1, v1
	v_mul_f32_e32 v66, 0xbfb8aa3b, v75
	v_mul_f32_e32 v67, 0xbfb8aa3b, v76
	v_exp_f32_e32 v68, v66
	v_add_f32_e32 v1, 1.0, v1
	v_rcp_f32_e32 v66, v1
	v_exp_f32_e32 v1, v67
	v_mul_f32_e32 v67, 0xbfb8aa3b, v77
	v_exp_f32_e32 v67, v67
	v_add_f32_e32 v70, 1.0, v68
	v_add_f32_e32 v1, 1.0, v1
	v_rcp_f32_e32 v68, v1
	v_add_f32_e32 v1, 1.0, v67
	v_rcp_f32_e32 v69, v1
	v_rcp_f32_e32 v67, v70
	v_pk_mul_f32 v[70:71], v[108:109], v[76:77]
	v_pk_mul_f32 v[72:73], v[106:107], v[74:75]
	v_pk_mul_f32 v[68:69], v[70:71], v[68:69]
	v_pk_mul_f32 v[66:67], v[72:73], v[66:67]
	v_mov_b32_e32 v74, 0
	ds_read_b128 v[98:101], v223 offset:528
	ds_read_b128 v[106:109], v223 offset:1552
	ds_read_b128 v[114:117], v223 offset:2576
	ds_read_b128 v[70:73], v223 offset:3600
	v_mov_b32_e32 v110, 0
	v_mov_b32_e32 v111, 0
	v_mov_b32_e32 v112, 0
	v_mov_b32_e32 v113, 0
	s_and_saveexec_b64 s[48:49], s[0:1]
	v_add_u32_e32 v1, s91, v218
	ds_read_b128 v[110:113], v1 offset:512
	s_or_b64 exec, exec, s[48:49]
	s_waitcnt lgkmcnt(0)
	v_pk_fma_f32 v[82:83], v[58:59], v[114:115], v[70:71]
	s_nop 4
	v_fmac_f32_dpp v82, v58, v106 row_shr:1 row_mask:0xf bank_mask:0xf
	v_pk_fma_f32 v[14:15], v[14:15], v[160:161], v[54:55]
	v_fmac_f32_dpp v82, v58, v98 row_shr:2 row_mask:0xf bank_mask:0xf
	s_nop 0
	v_fmac_f32_dpp v82, v14, v106 row_shl:15 row_mask:0xf bank_mask:0xf
	v_pk_fma_f32 v[84:85], v[60:61], v[116:117], v[72:73]
	v_fmac_f32_dpp v82, v14, v98 row_shl:14 row_mask:0xf bank_mask:0xf
	v_fmac_f32_dpp v83, v59, v107 row_shr:1 row_mask:0xf bank_mask:0xf
	v_mov_b32_e32 v122, v160
	v_fmac_f32_dpp v83, v59, v99 row_shr:2 row_mask:0xf bank_mask:0xf
	v_mov_b32_e32 v123, v160
	v_fmac_f32_dpp v83, v15, v107 row_shl:15 row_mask:0xf bank_mask:0xf
	v_pk_fma_f32 v[16:17], v[16:17], v[122:123], v[56:57]
	v_fmac_f32_dpp v83, v15, v99 row_shl:14 row_mask:0xf bank_mask:0xf
	v_fmac_f32_dpp v84, v60, v108 row_shr:1 row_mask:0xf bank_mask:0xf
	s_nop 0
	v_fmac_f32_dpp v84, v60, v100 row_shr:2 row_mask:0xf bank_mask:0xf
	v_pk_fma_f32 v[124:125], v[18:19], v[162:163], v[54:55]
	v_fmac_f32_dpp v84, v16, v108 row_shl:15 row_mask:0xf bank_mask:0xf
	v_pk_fma_f32 v[18:19], v[14:15], v[114:115], v[70:71]
	v_fmac_f32_dpp v84, v16, v100 row_shl:14 row_mask:0xf bank_mask:0xf
	v_fmac_f32_dpp v85, v61, v109 row_shr:1 row_mask:0xf bank_mask:0xf
	s_nop 0
	v_fmac_f32_dpp v85, v61, v101 row_shr:2 row_mask:0xf bank_mask:0xf
	v_mov_b32_e32 v120, v162
	v_fmac_f32_dpp v85, v17, v109 row_shl:15 row_mask:0xf bank_mask:0xf
	v_mov_b32_e32 v121, v162
	v_fmac_f32_dpp v85, v17, v101 row_shl:14 row_mask:0xf bank_mask:0xf
	v_pk_fma_f32 v[76:77], v[20:21], v[120:121], v[56:57]
	v_fmac_f32_dpp v18, v14, v106 row_shr:1 row_mask:0xf bank_mask:0xf
	v_pk_fma_f32 v[20:21], v[16:17], v[116:117], v[72:73]
	v_fmac_f32_dpp v18, v14, v98 row_shr:2 row_mask:0xf bank_mask:0xf
	s_nop 0
	v_fmac_f32_dpp v18, v124, v106 row_shl:15 row_mask:0xf bank_mask:0xf
	s_nop 0
	v_fmac_f32_dpp v18, v124, v98 row_shl:14 row_mask:0xf bank_mask:0xf
	v_fmac_f32_dpp v19, v15, v107 row_shr:1 row_mask:0xf bank_mask:0xf
	v_pk_fma_f32 v[22:23], v[22:23], v[158:159], v[54:55]
	v_fmac_f32_dpp v19, v15, v99 row_shr:2 row_mask:0xf bank_mask:0xf
	v_pk_fma_f32 v[14:15], v[124:125], v[114:115], v[70:71]
	v_fmac_f32_dpp v19, v125, v107 row_shl:15 row_mask:0xf bank_mask:0xf
	v_mov_b32_e32 v118, v158
	v_fmac_f32_dpp v19, v125, v99 row_shl:14 row_mask:0xf bank_mask:0xf
	v_fmac_f32_dpp v20, v16, v108 row_shr:1 row_mask:0xf bank_mask:0xf
	v_mov_b32_e32 v119, v158
	v_fmac_f32_dpp v20, v16, v100 row_shr:2 row_mask:0xf bank_mask:0xf
	s_nop 0
	v_fmac_f32_dpp v20, v76, v108 row_shl:15 row_mask:0xf bank_mask:0xf
	v_pk_fma_f32 v[24:25], v[24:25], v[118:119], v[56:57]
	v_fmac_f32_dpp v20, v76, v100 row_shl:14 row_mask:0xf bank_mask:0xf
	v_fmac_f32_dpp v21, v17, v109 row_shr:1 row_mask:0xf bank_mask:0xf
	v_pk_fma_f32 v[70:71], v[22:23], v[114:115], v[70:71]
	v_fmac_f32_dpp v21, v17, v101 row_shr:2 row_mask:0xf bank_mask:0xf
	v_pk_fma_f32 v[16:17], v[76:77], v[116:117], v[72:73]
	v_fmac_f32_dpp v21, v77, v109 row_shl:15 row_mask:0xf bank_mask:0xf
	s_nop 0
	v_fmac_f32_dpp v21, v77, v101 row_shl:14 row_mask:0xf bank_mask:0xf
	v_pk_fma_f32 v[72:73], v[24:25], v[116:117], v[72:73]
	v_fmac_f32_dpp v14, v124, v106 row_shr:1 row_mask:0xf bank_mask:0xf
	s_nop 0
	v_fmac_f32_dpp v14, v124, v98 row_shr:2 row_mask:0xf bank_mask:0xf
	v_mov_b32_e32 v75, 0
	v_fmac_f32_dpp v14, v22, v106 row_shl:15 row_mask:0xf bank_mask:0xf
	s_nop 0
	v_fmac_f32_dpp v14, v22, v98 row_shl:14 row_mask:0xf bank_mask:0xf
	v_fmac_f32_dpp v15, v125, v107 row_shr:1 row_mask:0xf bank_mask:0xf
	s_nop 0
	v_fmac_f32_dpp v15, v125, v99 row_shr:2 row_mask:0xf bank_mask:0xf
	s_nop 0
	v_fmac_f32_dpp v15, v23, v107 row_shl:15 row_mask:0xf bank_mask:0xf
	s_nop 0
	v_fmac_f32_dpp v15, v23, v99 row_shl:14 row_mask:0xf bank_mask:0xf
	v_fmac_f32_dpp v16, v76, v108 row_shr:1 row_mask:0xf bank_mask:0xf
	s_nop 0
	v_fmac_f32_dpp v16, v76, v100 row_shr:2 row_mask:0xf bank_mask:0xf
	v_mov_b32_e32 v76, 0
	v_fmac_f32_dpp v16, v24, v108 row_shl:15 row_mask:0xf bank_mask:0xf
	s_nop 0
	v_fmac_f32_dpp v16, v24, v100 row_shl:14 row_mask:0xf bank_mask:0xf
	v_fmac_f32_dpp v17, v77, v109 row_shr:1 row_mask:0xf bank_mask:0xf
	s_nop 0
	v_fmac_f32_dpp v17, v77, v101 row_shr:2 row_mask:0xf bank_mask:0xf
	v_mov_b32_e32 v77, 0
	v_fmac_f32_dpp v17, v25, v109 row_shl:15 row_mask:0xf bank_mask:0xf
	s_nop 0
	v_fmac_f32_dpp v17, v25, v101 row_shl:14 row_mask:0xf bank_mask:0xf
	s_nop 0
	v_fmac_f32_dpp v70, v22, v106 row_shr:1 row_mask:0xf bank_mask:0xf
	s_nop 0
	v_fmac_f32_dpp v70, v22, v98 row_shr:2 row_mask:0xf bank_mask:0xf
	s_nop 0
	v_fmac_f32_dpp v70, v110, v106 row_shl:15 row_mask:0xf bank_mask:0xf
	s_nop 0
	v_fmac_f32_dpp v70, v110, v98 row_shl:14 row_mask:0xf bank_mask:0xf
	v_fmac_f32_dpp v71, v23, v107 row_shr:1 row_mask:0xf bank_mask:0xf
	s_nop 0
	v_fmac_f32_dpp v71, v23, v99 row_shr:2 row_mask:0xf bank_mask:0xf
	s_nop 0
	v_fmac_f32_dpp v71, v111, v107 row_shl:15 row_mask:0xf bank_mask:0xf
	s_nop 0
	v_fmac_f32_dpp v71, v111, v99 row_shl:14 row_mask:0xf bank_mask:0xf
	v_fmac_f32_dpp v72, v24, v108 row_shr:1 row_mask:0xf bank_mask:0xf
	s_nop 0
	v_fmac_f32_dpp v72, v24, v100 row_shr:2 row_mask:0xf bank_mask:0xf
	s_nop 0
	v_fmac_f32_dpp v72, v112, v108 row_shl:15 row_mask:0xf bank_mask:0xf
	s_nop 0
	v_fmac_f32_dpp v72, v112, v100 row_shl:14 row_mask:0xf bank_mask:0xf
	v_fmac_f32_dpp v73, v25, v109 row_shr:1 row_mask:0xf bank_mask:0xf
	s_nop 0
	v_fmac_f32_dpp v73, v25, v101 row_shr:2 row_mask:0xf bank_mask:0xf
	s_nop 0
	v_fmac_f32_dpp v73, v113, v109 row_shl:15 row_mask:0xf bank_mask:0xf
	s_nop 0
	v_fmac_f32_dpp v73, v113, v101 row_shl:14 row_mask:0xf bank_mask:0xf
	s_nop 0
	ds_read_b128 v[54:57], v223 offset:16
	ds_read_b128 v[58:61], v223 offset:1040
	ds_read_b128 v[98:101], v223 offset:2064
	ds_read_b128 v[22:25], v223 offset:3088
	s_and_saveexec_b64 s[48:49], s[0:1]
	v_add_u32_e32 v1, 0, v218
	v_add_u32_e32 v1, 0x20000, v1
	ds_read_b128 v[74:77], v1
	s_or_b64 exec, exec, s[48:49]
	v_pk_fma_f32 v[106:107], v[8:9], v[120:121], v[32:33]
	v_pk_fma_f32 v[8:9], v[2:3], v[160:161], v[30:31]
	s_waitcnt lgkmcnt(0)
	v_pk_fma_f32 v[2:3], v[26:27], v[98:99], v[22:23]
	s_nop 4
	v_fmac_f32_dpp v2, v26, v58 row_shr:1 row_mask:0xf bank_mask:0xf
	s_nop 0
	v_fmac_f32_dpp v2, v26, v54 row_shr:2 row_mask:0xf bank_mask:0xf
	v_pk_fma_f32 v[108:109], v[6:7], v[162:163], v[30:31]
	v_fmac_f32_dpp v2, v8, v58 row_shl:15 row_mask:0xf bank_mask:0xf
	v_pk_fma_f32 v[6:7], v[4:5], v[122:123], v[32:33]
	v_fmac_f32_dpp v2, v8, v54 row_shl:14 row_mask:0xf bank_mask:0xf
	v_fmac_f32_dpp v3, v27, v59 row_shr:1 row_mask:0xf bank_mask:0xf
	v_pk_fma_f32 v[4:5], v[28:29], v[100:101], v[24:25]
	v_fmac_f32_dpp v3, v27, v55 row_shr:2 row_mask:0xf bank_mask:0xf
	v_mul_f32_e32 v1, 0xbfb8aa3b, v2
	v_fmac_f32_dpp v3, v9, v59 row_shl:15 row_mask:0xf bank_mask:0xf
	v_exp_f32_e32 v1, v1
	v_fmac_f32_dpp v3, v9, v55 row_shl:14 row_mask:0xf bank_mask:0xf
	v_fmac_f32_dpp v4, v28, v60 row_shr:1 row_mask:0xf bank_mask:0xf
	s_nop 0
	v_fmac_f32_dpp v4, v28, v56 row_shr:2 row_mask:0xf bank_mask:0xf
	v_add_f32_e32 v1, 1.0, v1
	v_fmac_f32_dpp v4, v6, v60 row_shl:15 row_mask:0xf bank_mask:0xf
	v_rcp_f32_e32 v26, v1
	v_fmac_f32_dpp v4, v6, v56 row_shl:14 row_mask:0xf bank_mask:0xf
	v_fmac_f32_dpp v5, v29, v61 row_shr:1 row_mask:0xf bank_mask:0xf
	v_mul_f32_e32 v1, 0xbfb8aa3b, v3
	v_fmac_f32_dpp v5, v29, v57 row_shr:2 row_mask:0xf bank_mask:0xf
	v_mul_f32_e32 v27, 0xbfb8aa3b, v4
	v_fmac_f32_dpp v5, v7, v61 row_shl:15 row_mask:0xf bank_mask:0xf
	v_exp_f32_e32 v27, v27
	v_fmac_f32_dpp v5, v7, v57 row_shl:14 row_mask:0xf bank_mask:0xf
	v_exp_f32_e32 v1, v1
	v_mul_f32_e32 v28, 0xbfb8aa3b, v5
	v_exp_f32_e32 v29, v28
	v_add_f32_e32 v27, 1.0, v27
	v_add_f32_e32 v1, 1.0, v1
	v_rcp_f32_e32 v28, v27
	v_add_f32_e32 v27, 1.0, v29
	v_rcp_f32_e32 v29, v27
	v_rcp_f32_e32 v27, v1
	v_pk_mul_f32 v[4:5], v[84:85], v[4:5]
	v_pk_mul_f32 v[2:3], v[82:83], v[2:3]
	v_pk_mul_f32 v[4:5], v[4:5], v[28:29]
	v_pk_mul_f32 v[2:3], v[2:3], v[26:27]
	v_pk_fma_f32 v[26:27], v[8:9], v[98:99], v[22:23]
	v_fmac_f32_dpp v26, v8, v58 row_shr:1 row_mask:0xf bank_mask:0xf
	s_nop 0
	v_fmac_f32_dpp v26, v8, v54 row_shr:2 row_mask:0xf bank_mask:0xf
	v_fma_f32 v8, v6, v100, v24
	v_fmac_f32_dpp v26, v108, v58 row_shl:15 row_mask:0xf bank_mask:0xf
	v_pk_fma_f32 v[10:11], v[10:11], v[158:159], v[30:31]
	v_fmac_f32_dpp v26, v108, v54 row_shl:14 row_mask:0xf bank_mask:0xf
	v_fmac_f32_dpp v27, v9, v59 row_shr:1 row_mask:0xf bank_mask:0xf
	v_pk_fma_f32 v[12:13], v[12:13], v[118:119], v[32:33]
	v_fmac_f32_dpp v27, v9, v55 row_shr:2 row_mask:0xf bank_mask:0xf
	v_mul_f32_e32 v1, 0xbfb8aa3b, v26
	v_fmac_f32_dpp v27, v109, v59 row_shl:15 row_mask:0xf bank_mask:0xf
	v_exp_f32_e32 v1, v1
	v_fmac_f32_dpp v27, v109, v55 row_shl:14 row_mask:0xf bank_mask:0xf
	v_fmac_f32_dpp v8, v6, v60 row_shr:1 row_mask:0xf bank_mask:0xf
	v_fma_f32 v9, v7, v101, v25
	v_fmac_f32_dpp v8, v6, v56 row_shr:2 row_mask:0xf bank_mask:0xf
	v_add_f32_e32 v1, 1.0, v1
	v_fmac_f32_dpp v8, v106, v60 row_shl:15 row_mask:0xf bank_mask:0xf
	v_rcp_f32_e32 v6, v1
	v_fmac_f32_dpp v8, v106, v56 row_shl:14 row_mask:0xf bank_mask:0xf
	v_fmac_f32_dpp v9, v7, v61 row_shr:1 row_mask:0xf bank_mask:0xf
	v_mul_f32_e32 v1, 0xbfb8aa3b, v27
	v_fmac_f32_dpp v9, v7, v57 row_shr:2 row_mask:0xf bank_mask:0xf
	v_mul_f32_e32 v7, 0xbfb8aa3b, v8
	v_fmac_f32_dpp v9, v107, v61 row_shl:15 row_mask:0xf bank_mask:0xf
	v_exp_f32_e32 v7, v7
	v_fmac_f32_dpp v9, v107, v57 row_shl:14 row_mask:0xf bank_mask:0xf
	v_exp_f32_e32 v1, v1
	v_mul_f32_e32 v28, 0xbfb8aa3b, v9
	v_exp_f32_e32 v29, v28
	v_add_f32_e32 v7, 1.0, v7
	v_add_f32_e32 v1, 1.0, v1
	v_rcp_f32_e32 v28, v7
	v_add_f32_e32 v7, 1.0, v29
	v_rcp_f32_e32 v29, v7
	v_rcp_f32_e32 v7, v1
	v_pk_mul_f32 v[8:9], v[20:21], v[8:9]
	v_pk_mul_f32 v[18:19], v[18:19], v[26:27]
	v_pk_mul_f32 v[8:9], v[8:9], v[28:29]
	v_pk_mul_f32 v[6:7], v[18:19], v[6:7]
	v_pk_fma_f32 v[18:19], v[108:109], v[98:99], v[22:23]
	v_fmac_f32_dpp v18, v108, v58 row_shr:1 row_mask:0xf bank_mask:0xf
	s_nop 0
	v_fmac_f32_dpp v18, v108, v54 row_shr:2 row_mask:0xf bank_mask:0xf
	v_pk_fma_f32 v[20:21], v[106:107], v[100:101], v[24:25]
	v_fmac_f32_dpp v18, v10, v58 row_shl:15 row_mask:0xf bank_mask:0xf
	s_nop 0
	v_fmac_f32_dpp v18, v10, v54 row_shl:14 row_mask:0xf bank_mask:0xf
	v_fmac_f32_dpp v19, v109, v59 row_shr:1 row_mask:0xf bank_mask:0xf
	v_pk_fma_f32 v[24:25], v[12:13], v[100:101], v[24:25]
	v_fmac_f32_dpp v19, v109, v55 row_shr:2 row_mask:0xf bank_mask:0xf
	v_mul_f32_e32 v1, 0xbfb8aa3b, v18
	v_fmac_f32_dpp v19, v11, v59 row_shl:15 row_mask:0xf bank_mask:0xf
	v_exp_f32_e32 v1, v1
	v_fmac_f32_dpp v19, v11, v55 row_shl:14 row_mask:0xf bank_mask:0xf
	v_fmac_f32_dpp v20, v106, v60 row_shr:1 row_mask:0xf bank_mask:0xf
	s_nop 0
	v_fmac_f32_dpp v20, v106, v56 row_shr:2 row_mask:0xf bank_mask:0xf
	v_add_f32_e32 v1, 1.0, v1
	v_fmac_f32_dpp v20, v12, v60 row_shl:15 row_mask:0xf bank_mask:0xf
	v_rcp_f32_e32 v26, v1
	v_fmac_f32_dpp v20, v12, v56 row_shl:14 row_mask:0xf bank_mask:0xf
	v_fmac_f32_dpp v21, v107, v61 row_shr:1 row_mask:0xf bank_mask:0xf
	v_mul_f32_e32 v1, 0xbfb8aa3b, v19
	v_fmac_f32_dpp v21, v107, v57 row_shr:2 row_mask:0xf bank_mask:0xf
	v_mul_f32_e32 v27, 0xbfb8aa3b, v20
	v_fmac_f32_dpp v21, v13, v61 row_shl:15 row_mask:0xf bank_mask:0xf
	v_exp_f32_e32 v27, v27
	v_fmac_f32_dpp v21, v13, v57 row_shl:14 row_mask:0xf bank_mask:0xf
	v_exp_f32_e32 v1, v1
	v_mul_f32_e32 v28, 0xbfb8aa3b, v21
	v_exp_f32_e32 v29, v28
	v_add_f32_e32 v27, 1.0, v27
	v_add_f32_e32 v1, 1.0, v1
	v_rcp_f32_e32 v28, v27
	v_add_f32_e32 v27, 1.0, v29
	v_rcp_f32_e32 v29, v27
	v_rcp_f32_e32 v27, v1
	v_pk_mul_f32 v[16:17], v[16:17], v[20:21]
	v_pk_mul_f32 v[14:15], v[14:15], v[18:19]
	v_pk_mul_f32 v[16:17], v[16:17], v[28:29]
	v_pk_mul_f32 v[14:15], v[14:15], v[26:27]
	v_pk_fma_f32 v[18:19], v[10:11], v[98:99], v[22:23]
	v_fmac_f32_dpp v18, v10, v58 row_shr:1 row_mask:0xf bank_mask:0xf
	s_nop 0
	v_fmac_f32_dpp v18, v10, v54 row_shr:2 row_mask:0xf bank_mask:0xf
	v_mov_b64_e32 v[22:23], s[66:67]
	v_fmac_f32_dpp v18, v74, v58 row_shl:15 row_mask:0xf bank_mask:0xf
	s_ashr_i32 s47, s46, 31
	v_fmac_f32_dpp v18, v74, v54 row_shl:14 row_mask:0xf bank_mask:0xf
	v_fmac_f32_dpp v19, v11, v59 row_shr:1 row_mask:0xf bank_mask:0xf
	s_andn2_b64 vcc, exec, s[4:5]
	v_fmac_f32_dpp v19, v11, v55 row_shr:2 row_mask:0xf bank_mask:0xf
	v_mul_f32_e32 v1, 0xbfb8aa3b, v18
	v_fmac_f32_dpp v19, v75, v59 row_shl:15 row_mask:0xf bank_mask:0xf
	v_exp_f32_e32 v1, v1
	v_fmac_f32_dpp v19, v75, v55 row_shl:14 row_mask:0xf bank_mask:0xf
	v_fmac_f32_dpp v24, v12, v60 row_shr:1 row_mask:0xf bank_mask:0xf
	s_mov_b64 s[4:5], -1
	v_fmac_f32_dpp v24, v12, v56 row_shr:2 row_mask:0xf bank_mask:0xf
	v_add_f32_e32 v1, 1.0, v1
	v_fmac_f32_dpp v24, v76, v60 row_shl:15 row_mask:0xf bank_mask:0xf
	v_rcp_f32_e32 v10, v1
	v_fmac_f32_dpp v24, v76, v56 row_shl:14 row_mask:0xf bank_mask:0xf
	v_fmac_f32_dpp v25, v13, v61 row_shr:1 row_mask:0xf bank_mask:0xf
	v_mul_f32_e32 v1, 0xbfb8aa3b, v19
	v_fmac_f32_dpp v25, v13, v57 row_shr:2 row_mask:0xf bank_mask:0xf
	v_mul_f32_e32 v11, 0xbfb8aa3b, v24
	v_fmac_f32_dpp v25, v77, v61 row_shl:15 row_mask:0xf bank_mask:0xf
	v_exp_f32_e32 v11, v11
	v_fmac_f32_dpp v25, v77, v57 row_shl:14 row_mask:0xf bank_mask:0xf
	v_exp_f32_e32 v1, v1
	v_mul_f32_e32 v12, 0xbfb8aa3b, v25
	v_exp_f32_e32 v13, v12
	v_add_f32_e32 v11, 1.0, v11
	v_add_f32_e32 v1, 1.0, v1
	v_rcp_f32_e32 v12, v11
	v_add_f32_e32 v11, 1.0, v13
	v_rcp_f32_e32 v13, v11
	v_rcp_f32_e32 v11, v1
	v_lshl_add_u32 v1, s28, 8, v185
	v_pk_mul_f32 v[20:21], v[72:73], v[24:25]
	v_mad_i64_i32 v[24:25], s[28:29], v1, s12, v[22:23]
	s_lshl_b64 s[28:29], s[46:47], 1
	v_pk_mul_f32 v[18:19], v[70:71], v[18:19]
	v_lshl_add_u64 v[24:25], v[24:25], 0, s[28:29]
	v_pk_mul_f32 v[12:13], v[20:21], v[12:13]
	v_pk_mul_f32 v[10:11], v[18:19], v[10:11]
	v_lshl_add_u64 v[24:25], v[24:25], 0, v[182:183]
	v_cvt_pk_bf16_f32 v18, v78, v79
	v_cvt_pk_bf16_f32 v19, v80, v81
	v_cvt_pk_bf16_f32 v20, v66, v67
	v_cvt_pk_bf16_f32 v21, v68, v69
	global_store_dwordx4 v[24:25], v[18:21], off
	v_or_b32_e32 v24, 16, v1
	v_mad_i64_i32 v[24:25], s[46:47], v24, s12, v[22:23]
	v_lshl_add_u64 v[24:25], v[24:25], 0, s[28:29]
	v_lshl_add_u64 v[24:25], v[24:25], 0, v[182:183]
	v_cvt_pk_bf16_f32 v18, v62, v63
	v_cvt_pk_bf16_f32 v19, v64, v65
	v_cvt_pk_bf16_f32 v20, v42, v43
	v_cvt_pk_bf16_f32 v21, v44, v45
	global_store_dwordx4 v[24:25], v[18:21], off
	v_or_b32_e32 v24, 32, v1
	v_mad_i64_i32 v[24:25], s[46:47], v24, s12, v[22:23]
	v_lshl_add_u64 v[24:25], v[24:25], 0, s[28:29]
	v_lshl_add_u64 v[24:25], v[24:25], 0, v[182:183]
	v_cvt_pk_bf16_f32 v18, v50, v51
	v_cvt_pk_bf16_f32 v19, v52, v53
	v_cvt_pk_bf16_f32 v20, v38, v39
	v_cvt_pk_bf16_f32 v21, v40, v41
	global_store_dwordx4 v[24:25], v[18:21], off
	v_or_b32_e32 v24, 48, v1
	v_mad_i64_i32 v[24:25], s[46:47], v24, s12, v[22:23]
	v_lshl_add_u64 v[24:25], v[24:25], 0, s[28:29]
	v_lshl_add_u64 v[24:25], v[24:25], 0, v[182:183]
	v_cvt_pk_bf16_f32 v18, v46, v47
	v_cvt_pk_bf16_f32 v19, v48, v49
	v_cvt_pk_bf16_f32 v20, v34, v35
	v_cvt_pk_bf16_f32 v21, v36, v37
	global_store_dwordx4 v[24:25], v[18:21], off
	v_add_u32_e32 v24, 0x80, v1
	s_nop 0
	v_cvt_pk_bf16_f32 v18, v102, v103
	v_cvt_pk_bf16_f32 v19, v104, v105
	v_cvt_pk_bf16_f32 v20, v10, v11
	v_mad_i64_i32 v[10:11], s[46:47], v24, s12, v[22:23]
	v_lshl_add_u64 v[10:11], v[10:11], 0, s[28:29]
	v_lshl_add_u64 v[10:11], v[10:11], 0, v[182:183]
	v_cvt_pk_bf16_f32 v21, v12, v13
	global_store_dwordx4 v[10:11], v[18:21], off
	v_cvt_pk_bf16_f32 v10, v94, v95
	v_cvt_pk_bf16_f32 v11, v96, v97
	v_cvt_pk_bf16_f32 v12, v14, v15
	v_add_u32_e32 v14, 0x90, v1
	v_mad_i64_i32 v[14:15], s[46:47], v14, s12, v[22:23]
	v_lshl_add_u64 v[14:15], v[14:15], 0, s[28:29]
	v_lshl_add_u64 v[14:15], v[14:15], 0, v[182:183]
	v_cvt_pk_bf16_f32 v13, v16, v17
	global_store_dwordx4 v[14:15], v[10:13], off
	s_nop 1
	v_cvt_pk_bf16_f32 v10, v90, v91
	v_cvt_pk_bf16_f32 v11, v92, v93
	v_cvt_pk_bf16_f32 v12, v6, v7
	v_add_u32_e32 v6, 0xa0, v1
	v_mad_i64_i32 v[6:7], s[46:47], v6, s12, v[22:23]
	v_lshl_add_u64 v[6:7], v[6:7], 0, s[28:29]
	v_lshl_add_u64 v[6:7], v[6:7], 0, v[182:183]
	v_add_u32_e32 v1, 0xb0, v1
	v_cvt_pk_bf16_f32 v13, v8, v9
	global_store_dwordx4 v[6:7], v[10:13], off
	v_cvt_pk_bf16_f32 v6, v86, v87
	v_cvt_pk_bf16_f32 v7, v88, v89
	v_cvt_pk_bf16_f32 v8, v2, v3
	v_mad_i64_i32 v[2:3], s[46:47], v1, s12, v[22:23]
	v_lshl_add_u64 v[2:3], v[2:3], 0, s[28:29]
	v_lshl_add_u64 v[2:3], v[2:3], 0, v[182:183]
	v_cvt_pk_bf16_f32 v9, v4, v5
	global_store_dwordx4 v[2:3], v[6:9], off
	s_cbranch_vccnz .LBB0_553
	s_andn2_b64 vcc, exec, s[16:17]
	s_mov_b32 s3, s40
	s_mov_b64 s[28:29], s[94:95]
	s_mov_b64 s[4:5], s[36:37]
	s_cbranch_vccnz .LBB0_590
	s_ashr_i32 s3, s40, 5
	s_mul_hi_i32 s4, s3, 0x5800
	s_mulk_i32 s3, 0x5800
	v_readlane_b32 s5, v255, 14
	s_add_u32 s28, s5, s3
	v_readlane_b32 s3, v255, 15
	s_addc_u32 s29, s3, s4
	s_mov_b32 s3, s38
	s_mov_b64 s[4:5], s[62:63]

.LBB0_1323:
	s_or_b64 exec, exec, s[52:53]
	s_waitcnt lgkmcnt(0)
	s_barrier
	ds_read_b128 v[150:153], v223 offset:512
	ds_read_b128 v[154:157], v223 offset:1536
	ds_read_b128 v[162:165], v223 offset:2560
	ds_read_b128 v[138:141], v223 offset:3584
	v_mov_b32_e32 v158, 0
	v_mov_b32_e32 v159, 0
	v_mov_b32_e32 v160, 0
	v_mov_b32_e32 v161, 0
	s_and_saveexec_b64 s[52:53], s[36:37]
	v_add_u32_e32 v147, s77, v215
	ds_read_b128 v[158:161], v147 offset:512
	s_or_b64 exec, exec, s[52:53]
	v_fmamk_f32 v146, v146, 0x3a800000, v222
	v_rsq_f32_e32 v200, v146
	s_waitcnt lgkmcnt(0)
	v_fma_f32 v146, v166, v162, v138
	v_lshl_add_u32 v147, s30, 1, v1
	s_nop 4
	v_fmac_f32_dpp v146, v166, v154 row_shr:1 row_mask:0xf bank_mask:0xf
	v_mad_i64_i32 v[208:209], s[52:53], v147, s65, 0
	v_fmamk_f32 v147, v149, 0x3a800000, v222
	v_fmac_f32_dpp v146, v166, v150 row_shr:2 row_mask:0xf bank_mask:0xf
	v_rsq_f32_e32 v198, v147
	v_pk_fma_f32 v[78:79], v[78:79], v[200:201], v[122:123] op_sel_hi:[1,0,1]
	v_fma_f32 v147, v167, v163, v139
	v_fmac_f32_dpp v146, v78, v154 row_shl:15 row_mask:0xf bank_mask:0xf
	v_fmamk_f32 v148, v148, 0x3a800000, v222
	v_fmac_f32_dpp v146, v78, v150 row_shl:14 row_mask:0xf bank_mask:0xf
	v_fmac_f32_dpp v147, v167, v155 row_shr:1 row_mask:0xf bank_mask:0xf
	v_rsq_f32_e32 v196, v148
	v_fmac_f32_dpp v147, v167, v151 row_shr:2 row_mask:0xf bank_mask:0xf
	v_pk_fma_f32 v[148:149], v[168:169], v[164:165], v[140:141]
	v_fmac_f32_dpp v147, v79, v155 row_shl:15 row_mask:0xf bank_mask:0xf
	v_pk_fma_f32 v[80:81], v[80:81], v[200:201], v[124:125] op_sel_hi:[1,0,1]
	v_fmac_f32_dpp v147, v79, v151 row_shl:14 row_mask:0xf bank_mask:0xf
	v_fmac_f32_dpp v148, v168, v156 row_shr:1 row_mask:0xf bank_mask:0xf
	s_nop 0
	v_fmac_f32_dpp v148, v168, v152 row_shr:2 row_mask:0xf bank_mask:0xf
	v_pk_fma_f32 v[224:225], v[130:131], v[198:199], v[122:123] op_sel_hi:[1,0,1]
	v_fmac_f32_dpp v148, v80, v156 row_shl:15 row_mask:0xf bank_mask:0xf
	v_pk_fma_f32 v[130:131], v[78:79], v[162:163], v[138:139]
	v_fmac_f32_dpp v148, v80, v152 row_shl:14 row_mask:0xf bank_mask:0xf
	v_fmac_f32_dpp v149, v169, v157 row_shr:1 row_mask:0xf bank_mask:0xf
	s_nop 0
	v_fmac_f32_dpp v149, v169, v153 row_shr:2 row_mask:0xf bank_mask:0xf
	v_pk_fma_f32 v[210:211], v[132:133], v[198:199], v[124:125] op_sel_hi:[1,0,1]
	v_fmac_f32_dpp v149, v81, v157 row_shl:15 row_mask:0xf bank_mask:0xf
	v_pk_fma_f32 v[132:133], v[80:81], v[164:165], v[140:141]
	v_fmac_f32_dpp v149, v81, v153 row_shl:14 row_mask:0xf bank_mask:0xf
	s_nop 0
	v_fmac_f32_dpp v130, v78, v154 row_shr:1 row_mask:0xf bank_mask:0xf
	v_pk_fma_f32 v[134:135], v[134:135], v[196:197], v[122:123] op_sel_hi:[1,0,1]
	v_fmac_f32_dpp v130, v78, v150 row_shr:2 row_mask:0xf bank_mask:0xf
	v_fma_f32 v78, v224, v162, v138
	v_fmac_f32_dpp v130, v224, v154 row_shl:15 row_mask:0xf bank_mask:0xf
	v_pk_fma_f32 v[136:137], v[136:137], v[196:197], v[124:125] op_sel_hi:[1,0,1]
	v_fmac_f32_dpp v130, v224, v150 row_shl:14 row_mask:0xf bank_mask:0xf
	v_fmac_f32_dpp v131, v79, v155 row_shr:1 row_mask:0xf bank_mask:0xf
	s_nop 0
	v_fmac_f32_dpp v131, v79, v151 row_shr:2 row_mask:0xf bank_mask:0xf
	v_fma_f32 v79, v225, v163, v139
	v_fmac_f32_dpp v131, v225, v155 row_shl:15 row_mask:0xf bank_mask:0xf
	v_pk_fma_f32 v[138:139], v[134:135], v[162:163], v[138:139]
	v_fmac_f32_dpp v131, v225, v151 row_shl:14 row_mask:0xf bank_mask:0xf
	v_fmac_f32_dpp v132, v80, v156 row_shr:1 row_mask:0xf bank_mask:0xf
	s_lshl_b32 s50, s50, 7
	v_fmac_f32_dpp v132, v80, v152 row_shr:2 row_mask:0xf bank_mask:0xf
	v_fma_f32 v80, v210, v164, v140
	v_fmac_f32_dpp v132, v210, v156 row_shl:15 row_mask:0xf bank_mask:0xf
	s_nop 0
	v_fmac_f32_dpp v132, v210, v152 row_shl:14 row_mask:0xf bank_mask:0xf
	v_fmac_f32_dpp v133, v81, v157 row_shr:1 row_mask:0xf bank_mask:0xf
	v_or_b32_e32 v202, s50, v186
	v_fmac_f32_dpp v133, v81, v153 row_shr:2 row_mask:0xf bank_mask:0xf
	v_fma_f32 v81, v211, v165, v141
	v_fmac_f32_dpp v133, v211, v157 row_shl:15 row_mask:0xf bank_mask:0xf
	v_pk_fma_f32 v[140:141], v[136:137], v[164:165], v[140:141]
	v_fmac_f32_dpp v133, v211, v153 row_shl:14 row_mask:0xf bank_mask:0xf
	v_ashrrev_i32_e32 v203, 31, v202
	v_fmac_f32_dpp v78, v224, v154 row_shr:1 row_mask:0xf bank_mask:0xf
	v_lshl_add_u64 v[168:169], s[28:29], 0, v[208:209]
	v_fmac_f32_dpp v78, v224, v150 row_shr:2 row_mask:0xf bank_mask:0xf
	v_lshl_add_u64 v[166:167], v[202:203], 2, v[168:169]
	v_fmac_f32_dpp v78, v134, v154 row_shl:15 row_mask:0xf bank_mask:0xf
	s_nop 0
	v_fmac_f32_dpp v78, v134, v150 row_shl:14 row_mask:0xf bank_mask:0xf
	v_fmac_f32_dpp v79, v225, v155 row_shr:1 row_mask:0xf bank_mask:0xf
	s_nop 0
	v_fmac_f32_dpp v79, v225, v151 row_shr:2 row_mask:0xf bank_mask:0xf
	s_nop 0
	v_fmac_f32_dpp v79, v135, v155 row_shl:15 row_mask:0xf bank_mask:0xf
	s_nop 0
	v_fmac_f32_dpp v79, v135, v151 row_shl:14 row_mask:0xf bank_mask:0xf
	v_fmac_f32_dpp v80, v210, v156 row_shr:1 row_mask:0xf bank_mask:0xf
	s_nop 0
	v_fmac_f32_dpp v80, v210, v152 row_shr:2 row_mask:0xf bank_mask:0xf
	s_nop 0
	v_fmac_f32_dpp v80, v136, v156 row_shl:15 row_mask:0xf bank_mask:0xf
	s_nop 0
	v_fmac_f32_dpp v80, v136, v152 row_shl:14 row_mask:0xf bank_mask:0xf
	v_fmac_f32_dpp v81, v211, v157 row_shr:1 row_mask:0xf bank_mask:0xf
	s_nop 0
	v_fmac_f32_dpp v81, v211, v153 row_shr:2 row_mask:0xf bank_mask:0xf
	s_nop 0
	v_fmac_f32_dpp v81, v137, v157 row_shl:15 row_mask:0xf bank_mask:0xf
	s_nop 0
	v_fmac_f32_dpp v81, v137, v153 row_shl:14 row_mask:0xf bank_mask:0xf
	s_nop 0
	v_fmac_f32_dpp v138, v134, v154 row_shr:1 row_mask:0xf bank_mask:0xf
	s_nop 0
	v_fmac_f32_dpp v138, v134, v150 row_shr:2 row_mask:0xf bank_mask:0xf
	s_nop 0
	v_fmac_f32_dpp v138, v158, v154 row_shl:15 row_mask:0xf bank_mask:0xf
	s_nop 0
	v_fmac_f32_dpp v138, v158, v150 row_shl:14 row_mask:0xf bank_mask:0xf
	v_fmac_f32_dpp v139, v135, v155 row_shr:1 row_mask:0xf bank_mask:0xf
	s_nop 0
	v_fmac_f32_dpp v139, v135, v151 row_shr:2 row_mask:0xf bank_mask:0xf
	s_nop 0
	v_fmac_f32_dpp v139, v159, v155 row_shl:15 row_mask:0xf bank_mask:0xf
	s_nop 0
	v_fmac_f32_dpp v139, v159, v151 row_shl:14 row_mask:0xf bank_mask:0xf
	v_fmac_f32_dpp v140, v136, v156 row_shr:1 row_mask:0xf bank_mask:0xf
	s_nop 0
	v_fmac_f32_dpp v140, v136, v152 row_shr:2 row_mask:0xf bank_mask:0xf
	s_nop 0
	v_fmac_f32_dpp v140, v160, v156 row_shl:15 row_mask:0xf bank_mask:0xf
	s_nop 0
	v_fmac_f32_dpp v140, v160, v152 row_shl:14 row_mask:0xf bank_mask:0xf
	v_fmac_f32_dpp v141, v137, v157 row_shr:1 row_mask:0xf bank_mask:0xf
	s_nop 0
	v_fmac_f32_dpp v141, v137, v153 row_shr:2 row_mask:0xf bank_mask:0xf
	s_nop 0
	v_fmac_f32_dpp v141, v161, v157 row_shl:15 row_mask:0xf bank_mask:0xf
	s_nop 0
	v_fmac_f32_dpp v141, v161, v153 row_shl:14 row_mask:0xf bank_mask:0xf
	s_and_saveexec_b64 s[52:53], s[38:39]
	s_cbranch_execz .LBB0_1327
	v_add_co_u32_e32 v134, vcc, 0x2000, v166
	s_nop 1
	v_addc_co_u32_e32 v135, vcc, 0, v167, vcc
	global_store_dwordx4 v[134:135], v[138:141], off offset:3072
.LBB0_1327:
	s_or_b64 exec, exec, s[52:53]
	s_nop 0
	ds_read_b128 v[150:153], v223
	ds_read_b128 v[154:157], v223 offset:1024
	ds_read_b128 v[162:165], v223 offset:2048
	ds_read_b128 v[134:137], v223 offset:3072
	v_mov_b32_e32 v158, 0
	v_mov_b32_e32 v159, 0
	v_mov_b32_e32 v160, 0
	v_mov_b32_e32 v161, 0
	s_and_saveexec_b64 s[52:53], s[36:37]
	v_add_u32_e32 v158, 0, v215
	v_add_u32_e32 v158, 0x20000, v158
	ds_read_b128 v[158:161], v158
	s_or_b64 exec, exec, s[52:53]
	v_mov_b32_e32 v197, v196
	v_mov_b32_e32 v201, v200
	v_pk_fma_f32 v[210:211], v[62:63], v[196:197], v[118:119]
	v_mov_b32_e32 v62, v198
	v_mov_b32_e32 v63, v198
	v_pk_fma_f32 v[62:63], v[52:53], v[62:63], v[120:121]
	v_pk_fma_f32 v[52:53], v[46:47], v[200:201], v[118:119]
	s_waitcnt lgkmcnt(0)
	v_pk_fma_f32 v[46:47], v[142:143], v[162:163], v[134:135]
	s_nop 4
	v_fmac_f32_dpp v46, v142, v154 row_shr:1 row_mask:0xf bank_mask:0xf
	s_nop 0
	v_fmac_f32_dpp v46, v142, v150 row_shr:2 row_mask:0xf bank_mask:0xf
	v_mov_b32_e32 v199, v198
	v_fmac_f32_dpp v46, v52, v154 row_shl:15 row_mask:0xf bank_mask:0xf
	v_mov_b32_e32 v208, v196
	v_mov_b32_e32 v209, v196
	v_fmac_f32_dpp v46, v52, v150 row_shl:14 row_mask:0xf bank_mask:0xf
	v_fmac_f32_dpp v47, v143, v155 row_shr:1 row_mask:0xf bank_mask:0xf
	v_pk_fma_f32 v[208:209], v[64:65], v[208:209], v[120:121]
	v_pk_fma_f32 v[64:65], v[50:51], v[198:199], v[118:119]
	v_mov_b32_e32 v50, v200
	v_mov_b32_e32 v51, v200
	v_fmac_f32_dpp v47, v143, v151 row_shr:2 row_mask:0xf bank_mask:0xf
	v_pk_fma_f32 v[50:51], v[48:49], v[50:51], v[120:121]
	v_fmac_f32_dpp v47, v53, v155 row_shl:15 row_mask:0xf bank_mask:0xf
	v_pk_fma_f32 v[48:49], v[144:145], v[164:165], v[136:137]
	v_fmac_f32_dpp v47, v53, v151 row_shl:14 row_mask:0xf bank_mask:0xf
	v_fmac_f32_dpp v48, v144, v156 row_shr:1 row_mask:0xf bank_mask:0xf
	s_nop 0
	v_fmac_f32_dpp v48, v144, v152 row_shr:2 row_mask:0xf bank_mask:0xf
	v_mul_f32_e32 v142, 0xbfb8aa3b, v46
	v_fmac_f32_dpp v48, v50, v156 row_shl:15 row_mask:0xf bank_mask:0xf
	v_mul_f32_e32 v143, 0xbfb8aa3b, v47
	v_fmac_f32_dpp v48, v50, v152 row_shl:14 row_mask:0xf bank_mask:0xf
	v_fmac_f32_dpp v49, v145, v157 row_shr:1 row_mask:0xf bank_mask:0xf
	v_exp_f32_e32 v142, v142
	v_fmac_f32_dpp v49, v145, v153 row_shr:2 row_mask:0xf bank_mask:0xf
	v_mul_f32_e32 v144, 0xbfb8aa3b, v48
	v_fmac_f32_dpp v49, v51, v157 row_shl:15 row_mask:0xf bank_mask:0xf
	v_exp_f32_e32 v143, v143
	v_fmac_f32_dpp v49, v51, v153 row_shl:14 row_mask:0xf bank_mask:0xf
	v_exp_f32_e32 v144, v144
	v_mul_f32_e32 v145, 0xbfb8aa3b, v49
	v_exp_f32_e32 v145, v145
	v_add_f32_e32 v142, 1.0, v142
	v_add_f32_e32 v143, 1.0, v143
	v_add_f32_e32 v144, 1.0, v144
	v_add_f32_e32 v145, 1.0, v145
	v_rcp_f32_e32 v142, v142
	v_rcp_f32_e32 v144, v144
	v_rcp_f32_e32 v145, v145
	v_rcp_f32_e32 v143, v143
	v_pk_mul_f32 v[48:49], v[148:149], v[48:49]
	v_pk_mul_f32 v[46:47], v[146:147], v[46:47]
	v_pk_mul_f32 v[48:49], v[48:49], v[144:145]
	v_pk_mul_f32 v[46:47], v[46:47], v[142:143]
	v_pk_fma_f32 v[142:143], v[52:53], v[162:163], v[134:135]
	v_fmac_f32_dpp v142, v52, v154 row_shr:1 row_mask:0xf bank_mask:0xf
	s_nop 0
	v_fmac_f32_dpp v142, v52, v150 row_shr:2 row_mask:0xf bank_mask:0xf
	s_nop 0
	v_fmac_f32_dpp v142, v64, v154 row_shl:15 row_mask:0xf bank_mask:0xf
	s_nop 0
	v_fmac_f32_dpp v142, v64, v150 row_shl:14 row_mask:0xf bank_mask:0xf
	v_fmac_f32_dpp v143, v53, v155 row_shr:1 row_mask:0xf bank_mask:0xf
	s_nop 0
	v_fmac_f32_dpp v143, v53, v151 row_shr:2 row_mask:0xf bank_mask:0xf
	v_pk_fma_f32 v[52:53], v[50:51], v[164:165], v[136:137]
	v_fmac_f32_dpp v143, v65, v155 row_shl:15 row_mask:0xf bank_mask:0xf
	s_nop 0
	v_fmac_f32_dpp v143, v65, v151 row_shl:14 row_mask:0xf bank_mask:0xf
	v_fmac_f32_dpp v52, v50, v156 row_shr:1 row_mask:0xf bank_mask:0xf
	s_nop 0
	v_fmac_f32_dpp v52, v50, v152 row_shr:2 row_mask:0xf bank_mask:0xf
	v_mul_f32_e32 v50, 0xbfb8aa3b, v142
	v_fmac_f32_dpp v52, v62, v156 row_shl:15 row_mask:0xf bank_mask:0xf
	v_exp_f32_e32 v50, v50
	v_fmac_f32_dpp v52, v62, v152 row_shl:14 row_mask:0xf bank_mask:0xf
	v_fmac_f32_dpp v53, v51, v157 row_shr:1 row_mask:0xf bank_mask:0xf
	v_pk_mul_f32 v[130:131], v[130:131], v[142:143]
	v_fmac_f32_dpp v53, v51, v153 row_shr:2 row_mask:0xf bank_mask:0xf
	v_mul_f32_e32 v51, 0xbfb8aa3b, v143
	v_fmac_f32_dpp v53, v63, v157 row_shl:15 row_mask:0xf bank_mask:0xf
	v_mul_f32_e32 v144, 0xbfb8aa3b, v52
	v_fmac_f32_dpp v53, v63, v153 row_shl:14 row_mask:0xf bank_mask:0xf
	v_exp_f32_e32 v51, v51
	v_mul_f32_e32 v145, 0xbfb8aa3b, v53
	v_exp_f32_e32 v144, v144
	v_exp_f32_e32 v145, v145
	v_add_f32_e32 v50, 1.0, v50
	v_add_f32_e32 v51, 1.0, v51
	v_add_f32_e32 v144, 1.0, v144
	v_add_f32_e32 v145, 1.0, v145
	v_rcp_f32_e32 v50, v50
	v_rcp_f32_e32 v144, v144
	v_rcp_f32_e32 v145, v145
	v_rcp_f32_e32 v51, v51
	v_pk_mul_f32 v[52:53], v[132:133], v[52:53]
	v_pk_mul_f32 v[50:51], v[130:131], v[50:51]
	v_pk_mul_f32 v[52:53], v[52:53], v[144:145]
	v_pk_fma_f32 v[130:131], v[64:65], v[162:163], v[134:135]
	v_fmac_f32_dpp v130, v64, v154 row_shr:1 row_mask:0xf bank_mask:0xf
	s_nop 0
	v_fmac_f32_dpp v130, v64, v150 row_shr:2 row_mask:0xf bank_mask:0xf
	s_nop 0
	v_fmac_f32_dpp v130, v210, v154 row_shl:15 row_mask:0xf bank_mask:0xf
	v_pk_fma_f32 v[134:135], v[210:211], v[162:163], v[134:135]
	v_fmac_f32_dpp v130, v210, v150 row_shl:14 row_mask:0xf bank_mask:0xf
	v_fmac_f32_dpp v131, v65, v155 row_shr:1 row_mask:0xf bank_mask:0xf
	s_nop 0
	v_fmac_f32_dpp v131, v65, v151 row_shr:2 row_mask:0xf bank_mask:0xf
	v_pk_fma_f32 v[64:65], v[62:63], v[164:165], v[136:137]
	v_fmac_f32_dpp v131, v211, v155 row_shl:15 row_mask:0xf bank_mask:0xf
	v_pk_fma_f32 v[136:137], v[208:209], v[164:165], v[136:137]
	v_fmac_f32_dpp v131, v211, v151 row_shl:14 row_mask:0xf bank_mask:0xf
	v_fmac_f32_dpp v64, v62, v156 row_shr:1 row_mask:0xf bank_mask:0xf
	s_nop 0
	v_fmac_f32_dpp v64, v62, v152 row_shr:2 row_mask:0xf bank_mask:0xf
	v_mul_f32_e32 v62, 0xbfb8aa3b, v130
	v_fmac_f32_dpp v64, v208, v156 row_shl:15 row_mask:0xf bank_mask:0xf
	v_exp_f32_e32 v62, v62
	v_fmac_f32_dpp v64, v208, v152 row_shl:14 row_mask:0xf bank_mask:0xf
	v_fmac_f32_dpp v65, v63, v157 row_shr:1 row_mask:0xf bank_mask:0xf
	v_pk_mul_f32 v[78:79], v[78:79], v[130:131]
	v_fmac_f32_dpp v65, v63, v153 row_shr:2 row_mask:0xf bank_mask:0xf
	v_mul_f32_e32 v63, 0xbfb8aa3b, v131
	v_fmac_f32_dpp v65, v209, v157 row_shl:15 row_mask:0xf bank_mask:0xf
	v_mul_f32_e32 v132, 0xbfb8aa3b, v64
	v_fmac_f32_dpp v65, v209, v153 row_shl:14 row_mask:0xf bank_mask:0xf
	v_exp_f32_e32 v63, v63
	v_mul_f32_e32 v133, 0xbfb8aa3b, v65
	v_exp_f32_e32 v132, v132
	v_exp_f32_e32 v133, v133
	v_add_f32_e32 v62, 1.0, v62
	v_add_f32_e32 v63, 1.0, v63
	v_add_f32_e32 v132, 1.0, v132
	v_add_f32_e32 v133, 1.0, v133
	v_rcp_f32_e32 v62, v62
	v_rcp_f32_e32 v132, v132
	v_rcp_f32_e32 v133, v133
	v_rcp_f32_e32 v63, v63
	v_pk_mul_f32 v[64:65], v[80:81], v[64:65]
	v_pk_mul_f32 v[62:63], v[78:79], v[62:63]
	v_pk_mul_f32 v[64:65], v[64:65], v[132:133]
	s_nop 0
	v_fmac_f32_dpp v134, v210, v154 row_shr:1 row_mask:0xf bank_mask:0xf
	s_nop 0
	v_fmac_f32_dpp v134, v210, v150 row_shr:2 row_mask:0xf bank_mask:0xf
	s_nop 0
	v_fmac_f32_dpp v134, v158, v154 row_shl:15 row_mask:0xf bank_mask:0xf
	s_nop 0
	v_fmac_f32_dpp v134, v158, v150 row_shl:14 row_mask:0xf bank_mask:0xf
	v_fmac_f32_dpp v135, v211, v155 row_shr:1 row_mask:0xf bank_mask:0xf
	s_nop 0
	v_fmac_f32_dpp v135, v211, v151 row_shr:2 row_mask:0xf bank_mask:0xf
	s_nop 0
	v_fmac_f32_dpp v135, v159, v155 row_shl:15 row_mask:0xf bank_mask:0xf
	s_nop 0
	v_fmac_f32_dpp v135, v159, v151 row_shl:14 row_mask:0xf bank_mask:0xf
	v_fmac_f32_dpp v136, v208, v156 row_shr:1 row_mask:0xf bank_mask:0xf
	s_nop 0
	v_fmac_f32_dpp v136, v208, v152 row_shr:2 row_mask:0xf bank_mask:0xf
	s_nop 0
	v_fmac_f32_dpp v136, v160, v156 row_shl:15 row_mask:0xf bank_mask:0xf
	s_nop 0
	v_fmac_f32_dpp v136, v160, v152 row_shl:14 row_mask:0xf bank_mask:0xf
	v_fmac_f32_dpp v137, v209, v157 row_shr:1 row_mask:0xf bank_mask:0xf
	s_nop 0
	v_fmac_f32_dpp v137, v209, v153 row_shr:2 row_mask:0xf bank_mask:0xf
	s_nop 0
	v_fmac_f32_dpp v137, v161, v157 row_shl:15 row_mask:0xf bank_mask:0xf
	s_nop 0
	v_fmac_f32_dpp v137, v161, v153 row_shl:14 row_mask:0xf bank_mask:0xf
	s_and_saveexec_b64 s[52:53], s[38:39]
	s_cbranch_execz .LBB0_1331
	global_store_dwordx4 v[166:167], v[134:137], off
.LBB0_1331:
	s_or_b64 exec, exec, s[52:53]
	v_mul_f32_e32 v78, 0xbfb8aa3b, v134
	v_mul_f32_e32 v79, 0xbfb8aa3b, v135
	v_mul_f32_e32 v80, 0xbfb8aa3b, v136
	v_mul_f32_e32 v81, 0xbfb8aa3b, v137
	v_exp_f32_e32 v78, v78
	v_exp_f32_e32 v79, v79
	v_exp_f32_e32 v80, v80
	v_exp_f32_e32 v81, v81
	v_add_f32_e32 v78, 1.0, v78
	v_add_f32_e32 v79, 1.0, v79
	v_add_f32_e32 v80, 1.0, v80
	v_add_f32_e32 v81, 1.0, v81
	v_rcp_f32_e32 v78, v78
	v_rcp_f32_e32 v80, v80
	v_rcp_f32_e32 v81, v81
	v_rcp_f32_e32 v79, v79
	v_pk_mul_f32 v[130:131], v[140:141], v[136:137]
	v_pk_mul_f32 v[132:133], v[138:139], v[134:135]
	v_pk_mul_f32 v[80:81], v[130:131], v[80:81]
	v_pk_mul_f32 v[78:79], v[132:133], v[78:79]
	v_mov_b32_e32 v134, 0
	ds_read_b128 v[142:145], v223 offset:512
	ds_read_b128 v[146:149], v223 offset:1536
	ds_read_b128 v[154:157], v223 offset:2560
	ds_read_b128 v[130:133], v223 offset:3584
	v_mov_b32_e32 v150, 0
	v_mov_b32_e32 v151, 0
	v_mov_b32_e32 v152, 0
	v_mov_b32_e32 v153, 0
	s_and_saveexec_b64 s[52:53], s[0:1]
	v_add_u32_e32 v135, s77, v216
	ds_read_b128 v[150:153], v135 offset:512
	s_or_b64 exec, exec, s[52:53]
	v_fmamk_f32 v136, v204, 0x3a800000, v222
	v_rsq_f32_e32 v160, v136
	s_waitcnt lgkmcnt(0)
	v_pk_fma_f32 v[138:139], v[126:127], v[154:155], v[130:131]
	s_nop 4
	v_fmac_f32_dpp v138, v126, v146 row_shr:1 row_mask:0xf bank_mask:0xf
	v_pk_fma_f32 v[102:103], v[102:103], v[160:161], v[122:123] op_sel_hi:[1,0,1]
	v_fmac_f32_dpp v138, v126, v142 row_shr:2 row_mask:0xf bank_mask:0xf
	s_nop 0
	v_fmac_f32_dpp v138, v102, v146 row_shl:15 row_mask:0xf bank_mask:0xf
	v_pk_fma_f32 v[140:141], v[128:129], v[156:157], v[132:133]
	v_fmac_f32_dpp v138, v102, v142 row_shl:14 row_mask:0xf bank_mask:0xf
	v_fmac_f32_dpp v139, v127, v147 row_shr:1 row_mask:0xf bank_mask:0xf
	v_fmamk_f32 v135, v206, 0x3a800000, v222
	v_fmac_f32_dpp v139, v127, v143 row_shr:2 row_mask:0xf bank_mask:0xf
	v_rsq_f32_e32 v158, v135
	v_fmac_f32_dpp v139, v103, v147 row_shl:15 row_mask:0xf bank_mask:0xf
	v_fmamk_f32 v135, v207, 0x3a800000, v222
	v_fmac_f32_dpp v139, v103, v143 row_shl:14 row_mask:0xf bank_mask:0xf
	v_fmac_f32_dpp v140, v128, v148 row_shr:1 row_mask:0xf bank_mask:0xf
	v_rsq_f32_e32 v162, v135
	v_fmac_f32_dpp v140, v128, v144 row_shr:2 row_mask:0xf bank_mask:0xf
	v_pk_fma_f32 v[104:105], v[104:105], v[160:161], v[124:125] op_sel_hi:[1,0,1]
	s_nop 0
	v_fmac_f32_dpp v140, v104, v148 row_shl:15 row_mask:0xf bank_mask:0xf
	v_pk_fma_f32 v[164:165], v[106:107], v[162:163], v[122:123] op_sel_hi:[1,0,1]
	v_fmac_f32_dpp v140, v104, v144 row_shl:14 row_mask:0xf bank_mask:0xf
	v_fmac_f32_dpp v141, v129, v149 row_shr:1 row_mask:0xf bank_mask:0xf
	v_pk_fma_f32 v[106:107], v[102:103], v[154:155], v[130:131]
	v_fmac_f32_dpp v141, v129, v145 row_shr:2 row_mask:0xf bank_mask:0xf
	s_nop 0
	v_fmac_f32_dpp v141, v105, v149 row_shl:15 row_mask:0xf bank_mask:0xf
	v_pk_fma_f32 v[136:137], v[108:109], v[162:163], v[124:125] op_sel_hi:[1,0,1]
	v_fmac_f32_dpp v141, v105, v145 row_shl:14 row_mask:0xf bank_mask:0xf
	v_pk_fma_f32 v[108:109], v[104:105], v[156:157], v[132:133]
	v_fmac_f32_dpp v106, v102, v146 row_shr:1 row_mask:0xf bank_mask:0xf
	s_nop 0
	v_fmac_f32_dpp v106, v102, v142 row_shr:2 row_mask:0xf bank_mask:0xf
	s_nop 0
	v_fmac_f32_dpp v106, v164, v146 row_shl:15 row_mask:0xf bank_mask:0xf
	v_pk_fma_f32 v[110:111], v[110:111], v[158:159], v[122:123] op_sel_hi:[1,0,1]
	v_fmac_f32_dpp v106, v164, v142 row_shl:14 row_mask:0xf bank_mask:0xf
	v_fmac_f32_dpp v107, v103, v147 row_shr:1 row_mask:0xf bank_mask:0xf
	v_pk_fma_f32 v[112:113], v[112:113], v[158:159], v[124:125] op_sel_hi:[1,0,1]
	v_fmac_f32_dpp v107, v103, v143 row_shr:2 row_mask:0xf bank_mask:0xf
	v_pk_fma_f32 v[102:103], v[164:165], v[154:155], v[130:131]
	v_fmac_f32_dpp v107, v165, v147 row_shl:15 row_mask:0xf bank_mask:0xf
	v_pk_fma_f32 v[130:131], v[110:111], v[154:155], v[130:131]
	v_fmac_f32_dpp v107, v165, v143 row_shl:14 row_mask:0xf bank_mask:0xf
	v_fmac_f32_dpp v108, v104, v148 row_shr:1 row_mask:0xf bank_mask:0xf
	s_nop 0
	v_fmac_f32_dpp v108, v104, v144 row_shr:2 row_mask:0xf bank_mask:0xf
	v_fma_f32 v104, v136, v156, v132
	v_fmac_f32_dpp v108, v136, v148 row_shl:15 row_mask:0xf bank_mask:0xf
	s_nop 0
	v_fmac_f32_dpp v108, v136, v144 row_shl:14 row_mask:0xf bank_mask:0xf
	v_fmac_f32_dpp v109, v105, v149 row_shr:1 row_mask:0xf bank_mask:0xf
	v_mov_b32_e32 v135, 0
	v_fmac_f32_dpp v109, v105, v145 row_shr:2 row_mask:0xf bank_mask:0xf
	v_fma_f32 v105, v137, v157, v133
	v_fmac_f32_dpp v109, v137, v149 row_shl:15 row_mask:0xf bank_mask:0xf
	v_pk_fma_f32 v[132:133], v[112:113], v[156:157], v[132:133]
	v_fmac_f32_dpp v109, v137, v145 row_shl:14 row_mask:0xf bank_mask:0xf
	s_nop 0
	v_fmac_f32_dpp v102, v164, v146 row_shr:1 row_mask:0xf bank_mask:0xf
	s_nop 0
	v_fmac_f32_dpp v102, v164, v142 row_shr:2 row_mask:0xf bank_mask:0xf
	s_nop 0
	v_fmac_f32_dpp v102, v110, v146 row_shl:15 row_mask:0xf bank_mask:0xf
	s_nop 0
	v_fmac_f32_dpp v102, v110, v142 row_shl:14 row_mask:0xf bank_mask:0xf
	v_fmac_f32_dpp v103, v165, v147 row_shr:1 row_mask:0xf bank_mask:0xf
	s_nop 0
	v_fmac_f32_dpp v103, v165, v143 row_shr:2 row_mask:0xf bank_mask:0xf
	s_nop 0
	v_fmac_f32_dpp v103, v111, v147 row_shl:15 row_mask:0xf bank_mask:0xf
	s_nop 0
	v_fmac_f32_dpp v103, v111, v143 row_shl:14 row_mask:0xf bank_mask:0xf
	v_fmac_f32_dpp v104, v136, v148 row_shr:1 row_mask:0xf bank_mask:0xf
	s_nop 0
	v_fmac_f32_dpp v104, v136, v144 row_shr:2 row_mask:0xf bank_mask:0xf
	v_mov_b32_e32 v136, 0
	v_fmac_f32_dpp v104, v112, v148 row_shl:15 row_mask:0xf bank_mask:0xf
	s_nop 0
	v_fmac_f32_dpp v104, v112, v144 row_shl:14 row_mask:0xf bank_mask:0xf
	v_fmac_f32_dpp v105, v137, v149 row_shr:1 row_mask:0xf bank_mask:0xf
	s_nop 0
	v_fmac_f32_dpp v105, v137, v145 row_shr:2 row_mask:0xf bank_mask:0xf
	v_mov_b32_e32 v137, 0
	v_fmac_f32_dpp v105, v113, v149 row_shl:15 row_mask:0xf bank_mask:0xf
	s_nop 0
	v_fmac_f32_dpp v105, v113, v145 row_shl:14 row_mask:0xf bank_mask:0xf
	s_nop 0
	v_fmac_f32_dpp v130, v110, v146 row_shr:1 row_mask:0xf bank_mask:0xf
	s_nop 0
	v_fmac_f32_dpp v130, v110, v142 row_shr:2 row_mask:0xf bank_mask:0xf
	s_nop 0
	v_fmac_f32_dpp v130, v150, v146 row_shl:15 row_mask:0xf bank_mask:0xf
	s_nop 0
	v_fmac_f32_dpp v130, v150, v142 row_shl:14 row_mask:0xf bank_mask:0xf
	v_fmac_f32_dpp v131, v111, v147 row_shr:1 row_mask:0xf bank_mask:0xf
	s_nop 0
	v_fmac_f32_dpp v131, v111, v143 row_shr:2 row_mask:0xf bank_mask:0xf
	s_nop 0
	v_fmac_f32_dpp v131, v151, v147 row_shl:15 row_mask:0xf bank_mask:0xf
	s_nop 0
	v_fmac_f32_dpp v131, v151, v143 row_shl:14 row_mask:0xf bank_mask:0xf
	v_fmac_f32_dpp v132, v112, v148 row_shr:1 row_mask:0xf bank_mask:0xf
	s_nop 0
	v_fmac_f32_dpp v132, v112, v144 row_shr:2 row_mask:0xf bank_mask:0xf
	s_nop 0
	v_fmac_f32_dpp v132, v152, v148 row_shl:15 row_mask:0xf bank_mask:0xf
	s_nop 0
	v_fmac_f32_dpp v132, v152, v144 row_shl:14 row_mask:0xf bank_mask:0xf
	v_fmac_f32_dpp v133, v113, v149 row_shr:1 row_mask:0xf bank_mask:0xf
	s_nop 0
	v_fmac_f32_dpp v133, v113, v145 row_shr:2 row_mask:0xf bank_mask:0xf
	s_nop 0
	v_fmac_f32_dpp v133, v153, v149 row_shl:15 row_mask:0xf bank_mask:0xf
	s_nop 0
	v_fmac_f32_dpp v133, v153, v145 row_shl:14 row_mask:0xf bank_mask:0xf
	s_nop 0
	ds_read_b128 v[122:125], v223
	ds_read_b128 v[126:129], v223 offset:1024
	ds_read_b128 v[142:145], v223 offset:2048
	ds_read_b128 v[110:113], v223 offset:3072
	s_and_saveexec_b64 s[52:53], s[0:1]
	v_add_u32_e32 v134, 0, v216
	v_add_u32_e32 v134, 0x20000, v134
	ds_read_b128 v[134:137], v134
	s_or_b64 exec, exec, s[52:53]
	v_mov_b32_e32 v159, v158
	v_mov_b32_e32 v161, v160
	v_pk_fma_f32 v[148:149], v[94:95], v[158:159], v[118:119]
	v_mov_b32_e32 v94, v162
	v_mov_b32_e32 v95, v162
	v_pk_fma_f32 v[94:95], v[92:93], v[94:95], v[120:121]
	v_pk_fma_f32 v[92:93], v[86:87], v[160:161], v[118:119]
	s_waitcnt lgkmcnt(0)
	v_pk_fma_f32 v[86:87], v[114:115], v[142:143], v[110:111]
	s_nop 4
	v_fmac_f32_dpp v86, v114, v126 row_shr:1 row_mask:0xf bank_mask:0xf
	s_nop 0
	v_fmac_f32_dpp v86, v114, v122 row_shr:2 row_mask:0xf bank_mask:0xf
	v_mov_b32_e32 v163, v162
	v_fmac_f32_dpp v86, v92, v126 row_shl:15 row_mask:0xf bank_mask:0xf
	v_mov_b32_e32 v146, v158
	v_mov_b32_e32 v147, v158
	v_fmac_f32_dpp v86, v92, v122 row_shl:14 row_mask:0xf bank_mask:0xf
	v_fmac_f32_dpp v87, v115, v127 row_shr:1 row_mask:0xf bank_mask:0xf
	v_pk_fma_f32 v[146:147], v[96:97], v[146:147], v[120:121]
	v_pk_fma_f32 v[96:97], v[90:91], v[162:163], v[118:119]
	v_mov_b32_e32 v90, v160
	v_mov_b32_e32 v91, v160
	v_fmac_f32_dpp v87, v115, v123 row_shr:2 row_mask:0xf bank_mask:0xf
	v_pk_fma_f32 v[90:91], v[88:89], v[90:91], v[120:121]
	v_fmac_f32_dpp v87, v93, v127 row_shl:15 row_mask:0xf bank_mask:0xf
	v_pk_fma_f32 v[88:89], v[116:117], v[144:145], v[112:113]
	v_fmac_f32_dpp v87, v93, v123 row_shl:14 row_mask:0xf bank_mask:0xf
	v_fmac_f32_dpp v88, v116, v128 row_shr:1 row_mask:0xf bank_mask:0xf
	s_nop 0
	v_fmac_f32_dpp v88, v116, v124 row_shr:2 row_mask:0xf bank_mask:0xf
	v_mul_f32_e32 v114, 0xbfb8aa3b, v86
	v_fmac_f32_dpp v88, v90, v128 row_shl:15 row_mask:0xf bank_mask:0xf
	v_mul_f32_e32 v115, 0xbfb8aa3b, v87
	v_fmac_f32_dpp v88, v90, v124 row_shl:14 row_mask:0xf bank_mask:0xf
	v_fmac_f32_dpp v89, v117, v129 row_shr:1 row_mask:0xf bank_mask:0xf
	v_exp_f32_e32 v114, v114
	v_fmac_f32_dpp v89, v117, v125 row_shr:2 row_mask:0xf bank_mask:0xf
	v_mul_f32_e32 v116, 0xbfb8aa3b, v88
	v_fmac_f32_dpp v89, v91, v129 row_shl:15 row_mask:0xf bank_mask:0xf
	v_exp_f32_e32 v115, v115
	v_fmac_f32_dpp v89, v91, v125 row_shl:14 row_mask:0xf bank_mask:0xf
	v_exp_f32_e32 v116, v116
	v_mul_f32_e32 v117, 0xbfb8aa3b, v89
	v_exp_f32_e32 v117, v117
	v_add_f32_e32 v114, 1.0, v114
	v_add_f32_e32 v115, 1.0, v115
	v_add_f32_e32 v116, 1.0, v116
	v_add_f32_e32 v117, 1.0, v117
	v_rcp_f32_e32 v114, v114
	v_rcp_f32_e32 v116, v116
	v_rcp_f32_e32 v117, v117
	v_rcp_f32_e32 v115, v115
	v_pk_mul_f32 v[88:89], v[140:141], v[88:89]
	v_pk_mul_f32 v[86:87], v[138:139], v[86:87]
	v_pk_mul_f32 v[88:89], v[88:89], v[116:117]
	v_pk_mul_f32 v[86:87], v[86:87], v[114:115]
	v_pk_fma_f32 v[114:115], v[92:93], v[142:143], v[110:111]
	v_fmac_f32_dpp v114, v92, v126 row_shr:1 row_mask:0xf bank_mask:0xf
	s_nop 0
	v_fmac_f32_dpp v114, v92, v122 row_shr:2 row_mask:0xf bank_mask:0xf
	s_nop 0
	v_fmac_f32_dpp v114, v96, v126 row_shl:15 row_mask:0xf bank_mask:0xf
	s_nop 0
	v_fmac_f32_dpp v114, v96, v122 row_shl:14 row_mask:0xf bank_mask:0xf
	v_fmac_f32_dpp v115, v93, v127 row_shr:1 row_mask:0xf bank_mask:0xf
	s_nop 0
	v_fmac_f32_dpp v115, v93, v123 row_shr:2 row_mask:0xf bank_mask:0xf
	v_pk_fma_f32 v[92:93], v[90:91], v[144:145], v[112:113]
	v_fmac_f32_dpp v115, v97, v127 row_shl:15 row_mask:0xf bank_mask:0xf
	s_nop 0
	v_fmac_f32_dpp v115, v97, v123 row_shl:14 row_mask:0xf bank_mask:0xf
	v_fmac_f32_dpp v92, v90, v128 row_shr:1 row_mask:0xf bank_mask:0xf
	s_nop 0
	v_fmac_f32_dpp v92, v90, v124 row_shr:2 row_mask:0xf bank_mask:0xf
	v_mul_f32_e32 v90, 0xbfb8aa3b, v114
	v_fmac_f32_dpp v92, v94, v128 row_shl:15 row_mask:0xf bank_mask:0xf
	v_exp_f32_e32 v90, v90
	v_fmac_f32_dpp v92, v94, v124 row_shl:14 row_mask:0xf bank_mask:0xf
	v_fmac_f32_dpp v93, v91, v129 row_shr:1 row_mask:0xf bank_mask:0xf
	v_pk_mul_f32 v[106:107], v[106:107], v[114:115]
	v_fmac_f32_dpp v93, v91, v125 row_shr:2 row_mask:0xf bank_mask:0xf
	v_mul_f32_e32 v91, 0xbfb8aa3b, v115
	v_fmac_f32_dpp v93, v95, v129 row_shl:15 row_mask:0xf bank_mask:0xf
	v_mul_f32_e32 v116, 0xbfb8aa3b, v92
	v_fmac_f32_dpp v93, v95, v125 row_shl:14 row_mask:0xf bank_mask:0xf
	v_exp_f32_e32 v91, v91
	v_mul_f32_e32 v117, 0xbfb8aa3b, v93
	v_exp_f32_e32 v116, v116
	v_exp_f32_e32 v117, v117
	v_add_f32_e32 v90, 1.0, v90
	v_add_f32_e32 v91, 1.0, v91
	v_add_f32_e32 v116, 1.0, v116
	v_add_f32_e32 v117, 1.0, v117
	v_rcp_f32_e32 v90, v90
	v_rcp_f32_e32 v116, v116
	v_rcp_f32_e32 v117, v117
	v_rcp_f32_e32 v91, v91
	v_pk_mul_f32 v[92:93], v[108:109], v[92:93]
	v_pk_mul_f32 v[90:91], v[106:107], v[90:91]
	v_pk_mul_f32 v[92:93], v[92:93], v[116:117]
	v_pk_fma_f32 v[106:107], v[96:97], v[142:143], v[110:111]
	v_fmac_f32_dpp v106, v96, v126 row_shr:1 row_mask:0xf bank_mask:0xf
	s_nop 0
	v_fmac_f32_dpp v106, v96, v122 row_shr:2 row_mask:0xf bank_mask:0xf
	v_fma_f32 v96, v94, v144, v112
	v_fmac_f32_dpp v106, v148, v126 row_shl:15 row_mask:0xf bank_mask:0xf
	s_nop 0
	v_fmac_f32_dpp v106, v148, v122 row_shl:14 row_mask:0xf bank_mask:0xf
	v_fmac_f32_dpp v107, v97, v127 row_shr:1 row_mask:0xf bank_mask:0xf
	s_nop 0
	v_fmac_f32_dpp v107, v97, v123 row_shr:2 row_mask:0xf bank_mask:0xf
	v_fma_f32 v97, v95, v145, v113
	v_fmac_f32_dpp v107, v149, v127 row_shl:15 row_mask:0xf bank_mask:0xf
	v_pk_fma_f32 v[112:113], v[146:147], v[144:145], v[112:113]
	v_fmac_f32_dpp v107, v149, v123 row_shl:14 row_mask:0xf bank_mask:0xf
	v_fmac_f32_dpp v96, v94, v128 row_shr:1 row_mask:0xf bank_mask:0xf
	s_nop 0
	v_fmac_f32_dpp v96, v94, v124 row_shr:2 row_mask:0xf bank_mask:0xf
	v_mul_f32_e32 v94, 0xbfb8aa3b, v106
	v_fmac_f32_dpp v96, v146, v128 row_shl:15 row_mask:0xf bank_mask:0xf
	v_exp_f32_e32 v94, v94
	v_fmac_f32_dpp v96, v146, v124 row_shl:14 row_mask:0xf bank_mask:0xf
	v_fmac_f32_dpp v97, v95, v129 row_shr:1 row_mask:0xf bank_mask:0xf
	v_pk_mul_f32 v[102:103], v[102:103], v[106:107]
	v_fmac_f32_dpp v97, v95, v125 row_shr:2 row_mask:0xf bank_mask:0xf
	v_mul_f32_e32 v95, 0xbfb8aa3b, v107
	v_fmac_f32_dpp v97, v147, v129 row_shl:15 row_mask:0xf bank_mask:0xf
	v_mul_f32_e32 v108, 0xbfb8aa3b, v96
	v_fmac_f32_dpp v97, v147, v125 row_shl:14 row_mask:0xf bank_mask:0xf
	v_exp_f32_e32 v95, v95
	v_mul_f32_e32 v109, 0xbfb8aa3b, v97
	v_exp_f32_e32 v108, v108
	v_exp_f32_e32 v109, v109
	v_add_f32_e32 v94, 1.0, v94
	v_add_f32_e32 v95, 1.0, v95
	v_add_f32_e32 v108, 1.0, v108
	v_add_f32_e32 v109, 1.0, v109
	v_rcp_f32_e32 v94, v94
	v_rcp_f32_e32 v108, v108
	v_rcp_f32_e32 v109, v109
	v_rcp_f32_e32 v95, v95
	v_pk_mul_f32 v[96:97], v[104:105], v[96:97]
	v_pk_mul_f32 v[94:95], v[102:103], v[94:95]
	v_pk_mul_f32 v[96:97], v[96:97], v[108:109]
	v_pk_fma_f32 v[102:103], v[148:149], v[142:143], v[110:111]
	v_fmac_f32_dpp v102, v148, v126 row_shr:1 row_mask:0xf bank_mask:0xf
	s_nop 0
	v_fmac_f32_dpp v102, v148, v122 row_shr:2 row_mask:0xf bank_mask:0xf
	s_nop 0
	v_fmac_f32_dpp v102, v134, v126 row_shl:15 row_mask:0xf bank_mask:0xf
	s_nop 0
	v_fmac_f32_dpp v102, v134, v122 row_shl:14 row_mask:0xf bank_mask:0xf
	v_fmac_f32_dpp v103, v149, v127 row_shr:1 row_mask:0xf bank_mask:0xf
	v_mov_b32_e32 v122, 0
	v_fmac_f32_dpp v103, v149, v123 row_shr:2 row_mask:0xf bank_mask:0xf
	v_mul_f32_e32 v104, 0xbfb8aa3b, v102
	v_fmac_f32_dpp v103, v135, v127 row_shl:15 row_mask:0xf bank_mask:0xf
	v_exp_f32_e32 v104, v104
	v_fmac_f32_dpp v103, v135, v123 row_shl:14 row_mask:0xf bank_mask:0xf
	v_fmac_f32_dpp v112, v146, v128 row_shr:1 row_mask:0xf bank_mask:0xf
	v_mov_b32_e32 v123, 0
	v_fmac_f32_dpp v112, v146, v124 row_shr:2 row_mask:0xf bank_mask:0xf
	v_add_f32_e32 v104, 1.0, v104
	v_fmac_f32_dpp v112, v136, v128 row_shl:15 row_mask:0xf bank_mask:0xf
	v_rcp_f32_e32 v106, v104
	v_fmac_f32_dpp v112, v136, v124 row_shl:14 row_mask:0xf bank_mask:0xf
	v_fmac_f32_dpp v113, v147, v129 row_shr:1 row_mask:0xf bank_mask:0xf
	v_mul_f32_e32 v104, 0xbfb8aa3b, v103
	v_fmac_f32_dpp v113, v147, v125 row_shr:2 row_mask:0xf bank_mask:0xf
	v_mul_f32_e32 v105, 0xbfb8aa3b, v112
	v_fmac_f32_dpp v113, v137, v129 row_shl:15 row_mask:0xf bank_mask:0xf
	v_exp_f32_e32 v104, v104
	v_fmac_f32_dpp v113, v137, v125 row_shl:14 row_mask:0xf bank_mask:0xf
	v_exp_f32_e32 v105, v105
	v_mul_f32_e32 v107, 0xbfb8aa3b, v113
	v_exp_f32_e32 v107, v107
	v_add_f32_e32 v108, 1.0, v104
	v_add_f32_e32 v104, 1.0, v105
	v_rcp_f32_e32 v104, v104
	v_add_f32_e32 v105, 1.0, v107
	v_rcp_f32_e32 v105, v105
	v_rcp_f32_e32 v107, v108
	v_pk_mul_f32 v[108:109], v[132:133], v[112:113]
	v_pk_mul_f32 v[102:103], v[130:131], v[102:103]
	v_pk_mul_f32 v[104:105], v[108:109], v[104:105]
	v_pk_mul_f32 v[102:103], v[102:103], v[106:107]
	v_mov_b32_e32 v124, 0
	ds_read_b128 v[114:117], v223 offset:528
	ds_read_b128 v[118:121], v223 offset:1552
	ds_read_b128 v[126:129], v223 offset:2576
	ds_read_b128 v[106:109], v223 offset:3600
	v_mov_b32_e32 v125, 0
	s_and_saveexec_b64 s[52:53], s[36:37]
	v_add_u32_e32 v110, s77, v217
	ds_read_b128 v[122:125], v110 offset:512
	s_or_b64 exec, exec, s[52:53]
	v_mov_b32_e32 v110, v196
	v_mov_b32_e32 v111, v196
	v_pk_fma_f32 v[76:77], v[76:77], v[110:111], v[56:57]
	v_mov_b32_e32 v110, v198
	v_mov_b32_e32 v111, v198
	v_pk_fma_f32 v[130:131], v[72:73], v[110:111], v[56:57]
	s_waitcnt lgkmcnt(0)
	v_pk_fma_f32 v[110:111], v[98:99], v[126:127], v[106:107]
	s_nop 4
	v_fmac_f32_dpp v110, v98, v118 row_shr:1 row_mask:0xf bank_mask:0xf
	v_pk_fma_f32 v[66:67], v[66:67], v[200:201], v[54:55]
	v_fmac_f32_dpp v110, v98, v114 row_shr:2 row_mask:0xf bank_mask:0xf
	s_nop 0
	v_fmac_f32_dpp v110, v66, v118 row_shl:15 row_mask:0xf bank_mask:0xf
	v_pk_fma_f32 v[112:113], v[100:101], v[128:129], v[108:109]
	v_fmac_f32_dpp v110, v66, v114 row_shl:14 row_mask:0xf bank_mask:0xf
	v_fmac_f32_dpp v111, v99, v119 row_shr:1 row_mask:0xf bank_mask:0xf
	v_pk_fma_f32 v[132:133], v[70:71], v[198:199], v[54:55]
	v_fmac_f32_dpp v111, v99, v115 row_shr:2 row_mask:0xf bank_mask:0xf
	v_mov_b32_e32 v70, v200
	v_fmac_f32_dpp v111, v67, v119 row_shl:15 row_mask:0xf bank_mask:0xf
	v_mov_b32_e32 v71, v200
	v_fmac_f32_dpp v111, v67, v115 row_shl:14 row_mask:0xf bank_mask:0xf
	v_fmac_f32_dpp v112, v100, v120 row_shr:1 row_mask:0xf bank_mask:0xf
	v_pk_fma_f32 v[68:69], v[68:69], v[70:71], v[56:57]
	v_fmac_f32_dpp v112, v100, v116 row_shr:2 row_mask:0xf bank_mask:0xf
	s_nop 0
	v_fmac_f32_dpp v112, v68, v120 row_shl:15 row_mask:0xf bank_mask:0xf
	v_pk_fma_f32 v[70:71], v[66:67], v[126:127], v[106:107]
	v_fmac_f32_dpp v112, v68, v116 row_shl:14 row_mask:0xf bank_mask:0xf
	v_fmac_f32_dpp v113, v101, v121 row_shr:1 row_mask:0xf bank_mask:0xf
	s_nop 0
	v_fmac_f32_dpp v113, v101, v117 row_shr:2 row_mask:0xf bank_mask:0xf
	v_pk_fma_f32 v[72:73], v[68:69], v[128:129], v[108:109]
	v_fmac_f32_dpp v113, v69, v121 row_shl:15 row_mask:0xf bank_mask:0xf
	s_nop 0
	v_fmac_f32_dpp v113, v69, v117 row_shl:14 row_mask:0xf bank_mask:0xf
	v_pk_fma_f32 v[74:75], v[74:75], v[196:197], v[54:55]
	v_fmac_f32_dpp v70, v66, v118 row_shr:1 row_mask:0xf bank_mask:0xf
	s_nop 0
	v_fmac_f32_dpp v70, v66, v114 row_shr:2 row_mask:0xf bank_mask:0xf
	v_fma_f32 v66, v132, v126, v106
	v_fmac_f32_dpp v70, v132, v118 row_shl:15 row_mask:0xf bank_mask:0xf
	s_nop 0
	v_fmac_f32_dpp v70, v132, v114 row_shl:14 row_mask:0xf bank_mask:0xf
	v_fmac_f32_dpp v71, v67, v119 row_shr:1 row_mask:0xf bank_mask:0xf
	s_nop 0
	v_fmac_f32_dpp v71, v67, v115 row_shr:2 row_mask:0xf bank_mask:0xf
	v_fma_f32 v67, v133, v127, v107
	v_fmac_f32_dpp v71, v133, v119 row_shl:15 row_mask:0xf bank_mask:0xf
	v_pk_fma_f32 v[106:107], v[74:75], v[126:127], v[106:107]
	v_fmac_f32_dpp v71, v133, v115 row_shl:14 row_mask:0xf bank_mask:0xf
	v_fmac_f32_dpp v72, v68, v120 row_shr:1 row_mask:0xf bank_mask:0xf
	s_nop 0
	v_fmac_f32_dpp v72, v68, v116 row_shr:2 row_mask:0xf bank_mask:0xf
	v_fma_f32 v68, v130, v128, v108
	v_fmac_f32_dpp v72, v130, v120 row_shl:15 row_mask:0xf bank_mask:0xf
	s_nop 0
	v_fmac_f32_dpp v72, v130, v116 row_shl:14 row_mask:0xf bank_mask:0xf
	v_fmac_f32_dpp v73, v69, v121 row_shr:1 row_mask:0xf bank_mask:0xf
	s_nop 0
	v_fmac_f32_dpp v73, v69, v117 row_shr:2 row_mask:0xf bank_mask:0xf
	v_fma_f32 v69, v131, v129, v109
	v_fmac_f32_dpp v73, v131, v121 row_shl:15 row_mask:0xf bank_mask:0xf
	v_pk_fma_f32 v[108:109], v[76:77], v[128:129], v[108:109]
	v_fmac_f32_dpp v73, v131, v117 row_shl:14 row_mask:0xf bank_mask:0xf
	s_nop 0
	v_fmac_f32_dpp v66, v132, v118 row_shr:1 row_mask:0xf bank_mask:0xf
	s_nop 0
	v_fmac_f32_dpp v66, v132, v114 row_shr:2 row_mask:0xf bank_mask:0xf
	s_nop 0
	v_fmac_f32_dpp v66, v74, v118 row_shl:15 row_mask:0xf bank_mask:0xf
	s_nop 0
	v_fmac_f32_dpp v66, v74, v114 row_shl:14 row_mask:0xf bank_mask:0xf
	v_fmac_f32_dpp v67, v133, v119 row_shr:1 row_mask:0xf bank_mask:0xf
	s_nop 0
	v_fmac_f32_dpp v67, v133, v115 row_shr:2 row_mask:0xf bank_mask:0xf
	s_nop 0
	v_fmac_f32_dpp v67, v75, v119 row_shl:15 row_mask:0xf bank_mask:0xf
	s_nop 0
	v_fmac_f32_dpp v67, v75, v115 row_shl:14 row_mask:0xf bank_mask:0xf
	v_fmac_f32_dpp v68, v130, v120 row_shr:1 row_mask:0xf bank_mask:0xf
	s_nop 0
	v_fmac_f32_dpp v68, v130, v116 row_shr:2 row_mask:0xf bank_mask:0xf
	s_nop 0
	v_fmac_f32_dpp v68, v76, v120 row_shl:15 row_mask:0xf bank_mask:0xf
	s_nop 0
	v_fmac_f32_dpp v68, v76, v116 row_shl:14 row_mask:0xf bank_mask:0xf
	v_fmac_f32_dpp v69, v131, v121 row_shr:1 row_mask:0xf bank_mask:0xf
	s_nop 0
	v_fmac_f32_dpp v69, v131, v117 row_shr:2 row_mask:0xf bank_mask:0xf
	s_nop 0
	v_fmac_f32_dpp v69, v77, v121 row_shl:15 row_mask:0xf bank_mask:0xf
	s_nop 0
	v_fmac_f32_dpp v69, v77, v117 row_shl:14 row_mask:0xf bank_mask:0xf
	s_nop 0
	v_fmac_f32_dpp v106, v74, v118 row_shr:1 row_mask:0xf bank_mask:0xf
	s_nop 0
	v_fmac_f32_dpp v106, v74, v114 row_shr:2 row_mask:0xf bank_mask:0xf
	s_nop 0
	v_fmac_f32_dpp v106, v122, v118 row_shl:15 row_mask:0xf bank_mask:0xf
	s_nop 0
	v_fmac_f32_dpp v106, v122, v114 row_shl:14 row_mask:0xf bank_mask:0xf
	v_fmac_f32_dpp v107, v75, v119 row_shr:1 row_mask:0xf bank_mask:0xf
	s_nop 0
	v_fmac_f32_dpp v107, v75, v115 row_shr:2 row_mask:0xf bank_mask:0xf
	s_nop 0
	v_fmac_f32_dpp v107, v123, v119 row_shl:15 row_mask:0xf bank_mask:0xf
	s_nop 0
	v_fmac_f32_dpp v107, v123, v115 row_shl:14 row_mask:0xf bank_mask:0xf
	v_fmac_f32_dpp v108, v76, v120 row_shr:1 row_mask:0xf bank_mask:0xf
	s_nop 0
	v_fmac_f32_dpp v108, v76, v116 row_shr:2 row_mask:0xf bank_mask:0xf
	s_nop 0
	v_fmac_f32_dpp v108, v124, v120 row_shl:15 row_mask:0xf bank_mask:0xf
	s_nop 0
	v_fmac_f32_dpp v108, v124, v116 row_shl:14 row_mask:0xf bank_mask:0xf
	v_fmac_f32_dpp v109, v77, v121 row_shr:1 row_mask:0xf bank_mask:0xf
	s_nop 0
	v_fmac_f32_dpp v109, v77, v117 row_shr:2 row_mask:0xf bank_mask:0xf
	s_nop 0
	v_fmac_f32_dpp v109, v125, v121 row_shl:15 row_mask:0xf bank_mask:0xf
	s_nop 0
	v_fmac_f32_dpp v109, v125, v117 row_shl:14 row_mask:0xf bank_mask:0xf
	s_and_saveexec_b64 s[52:53], s[38:39]
	s_cbranch_execz .LBB0_1339
	v_or_b32_e32 v74, 4, v202
	v_ashrrev_i32_e32 v75, 31, v74
	v_lshl_add_u64 v[74:75], v[74:75], 2, v[168:169]
	v_add_co_u32_e32 v74, vcc, 0x2000, v74
	s_nop 1
	v_addc_co_u32_e32 v75, vcc, 0, v75, vcc
	global_store_dwordx4 v[74:75], v[106:109], off offset:3072
.LBB0_1339:
	s_or_b64 exec, exec, s[52:53]
	s_nop 0
	ds_read_b128 v[98:101], v223 offset:16
	ds_read_b128 v[114:117], v223 offset:1040
	ds_read_b128 v[122:125], v223 offset:2064
	ds_read_b128 v[74:77], v223 offset:3088
	v_mov_b32_e32 v118, 0
	v_mov_b32_e32 v119, 0
	v_mov_b32_e32 v120, 0
	v_mov_b32_e32 v121, 0
	s_and_saveexec_b64 s[52:53], s[36:37]
	v_add_u32_e32 v118, 0, v217
	v_add_u32_e32 v118, 0x20000, v118
	ds_read_b128 v[118:121], v118
	s_or_b64 exec, exec, s[52:53]
	v_pk_fma_f32 v[128:129], v[42:43], v[196:197], v[30:31]
	v_mov_b32_e32 v42, v198
	v_mov_b32_e32 v43, v198
	v_pk_fma_f32 v[42:43], v[40:41], v[42:43], v[32:33]
	v_pk_fma_f32 v[40:41], v[34:35], v[200:201], v[30:31]
	s_waitcnt lgkmcnt(0)
	v_pk_fma_f32 v[34:35], v[82:83], v[122:123], v[74:75]
	s_nop 4
	v_fmac_f32_dpp v34, v82, v114 row_shr:1 row_mask:0xf bank_mask:0xf
	s_nop 0
	v_fmac_f32_dpp v34, v82, v98 row_shr:2 row_mask:0xf bank_mask:0xf
	v_mov_b32_e32 v126, v196
	v_fmac_f32_dpp v34, v40, v114 row_shl:15 row_mask:0xf bank_mask:0xf
	v_mov_b32_e32 v127, v196
	v_fmac_f32_dpp v34, v40, v98 row_shl:14 row_mask:0xf bank_mask:0xf
	v_fmac_f32_dpp v35, v83, v115 row_shr:1 row_mask:0xf bank_mask:0xf
	v_pk_fma_f32 v[126:127], v[44:45], v[126:127], v[32:33]
	v_pk_fma_f32 v[44:45], v[38:39], v[198:199], v[30:31]
	v_mov_b32_e32 v38, v200
	v_mov_b32_e32 v39, v200
	v_fmac_f32_dpp v35, v83, v99 row_shr:2 row_mask:0xf bank_mask:0xf
	v_pk_fma_f32 v[38:39], v[36:37], v[38:39], v[32:33]
	v_fmac_f32_dpp v35, v41, v115 row_shl:15 row_mask:0xf bank_mask:0xf
	v_pk_fma_f32 v[36:37], v[84:85], v[124:125], v[76:77]
	v_fmac_f32_dpp v35, v41, v99 row_shl:14 row_mask:0xf bank_mask:0xf
	v_fmac_f32_dpp v36, v84, v116 row_shr:1 row_mask:0xf bank_mask:0xf
	s_nop 0
	v_fmac_f32_dpp v36, v84, v100 row_shr:2 row_mask:0xf bank_mask:0xf
	v_mul_f32_e32 v82, 0xbfb8aa3b, v34
	v_fmac_f32_dpp v36, v38, v116 row_shl:15 row_mask:0xf bank_mask:0xf
	v_mul_f32_e32 v83, 0xbfb8aa3b, v35
	v_fmac_f32_dpp v36, v38, v100 row_shl:14 row_mask:0xf bank_mask:0xf
	v_fmac_f32_dpp v37, v85, v117 row_shr:1 row_mask:0xf bank_mask:0xf
	v_exp_f32_e32 v82, v82
	v_fmac_f32_dpp v37, v85, v101 row_shr:2 row_mask:0xf bank_mask:0xf
	v_mul_f32_e32 v84, 0xbfb8aa3b, v36
	v_fmac_f32_dpp v37, v39, v117 row_shl:15 row_mask:0xf bank_mask:0xf
	v_exp_f32_e32 v83, v83
	v_fmac_f32_dpp v37, v39, v101 row_shl:14 row_mask:0xf bank_mask:0xf
	v_exp_f32_e32 v84, v84
	v_mul_f32_e32 v85, 0xbfb8aa3b, v37
	v_exp_f32_e32 v85, v85
	v_add_f32_e32 v82, 1.0, v82
	v_add_f32_e32 v83, 1.0, v83
	v_add_f32_e32 v84, 1.0, v84
	v_add_f32_e32 v85, 1.0, v85
	v_rcp_f32_e32 v82, v82
	v_rcp_f32_e32 v84, v84
	v_rcp_f32_e32 v85, v85
	v_rcp_f32_e32 v83, v83
	v_pk_mul_f32 v[36:37], v[112:113], v[36:37]
	v_pk_mul_f32 v[34:35], v[110:111], v[34:35]
	v_pk_mul_f32 v[36:37], v[36:37], v[84:85]
	v_pk_mul_f32 v[34:35], v[34:35], v[82:83]
	v_pk_fma_f32 v[82:83], v[40:41], v[122:123], v[74:75]
	v_fmac_f32_dpp v82, v40, v114 row_shr:1 row_mask:0xf bank_mask:0xf
	s_nop 0
	v_fmac_f32_dpp v82, v40, v98 row_shr:2 row_mask:0xf bank_mask:0xf
	s_nop 0
	v_fmac_f32_dpp v82, v44, v114 row_shl:15 row_mask:0xf bank_mask:0xf
	s_nop 0
	v_fmac_f32_dpp v82, v44, v98 row_shl:14 row_mask:0xf bank_mask:0xf
	v_fmac_f32_dpp v83, v41, v115 row_shr:1 row_mask:0xf bank_mask:0xf
	s_nop 0
	v_fmac_f32_dpp v83, v41, v99 row_shr:2 row_mask:0xf bank_mask:0xf
	v_pk_fma_f32 v[40:41], v[38:39], v[124:125], v[76:77]
	v_fmac_f32_dpp v83, v45, v115 row_shl:15 row_mask:0xf bank_mask:0xf
	s_nop 0
	v_fmac_f32_dpp v83, v45, v99 row_shl:14 row_mask:0xf bank_mask:0xf
	v_fmac_f32_dpp v40, v38, v116 row_shr:1 row_mask:0xf bank_mask:0xf
	s_nop 0
	v_fmac_f32_dpp v40, v38, v100 row_shr:2 row_mask:0xf bank_mask:0xf
	v_mul_f32_e32 v38, 0xbfb8aa3b, v82
	v_fmac_f32_dpp v40, v42, v116 row_shl:15 row_mask:0xf bank_mask:0xf
	v_exp_f32_e32 v38, v38
	v_fmac_f32_dpp v40, v42, v100 row_shl:14 row_mask:0xf bank_mask:0xf
	v_fmac_f32_dpp v41, v39, v117 row_shr:1 row_mask:0xf bank_mask:0xf
	v_pk_mul_f32 v[70:71], v[70:71], v[82:83]
	v_fmac_f32_dpp v41, v39, v101 row_shr:2 row_mask:0xf bank_mask:0xf
	v_mul_f32_e32 v39, 0xbfb8aa3b, v83
	v_fmac_f32_dpp v41, v43, v117 row_shl:15 row_mask:0xf bank_mask:0xf
	v_mul_f32_e32 v84, 0xbfb8aa3b, v40
	v_fmac_f32_dpp v41, v43, v101 row_shl:14 row_mask:0xf bank_mask:0xf
	v_exp_f32_e32 v39, v39
	v_mul_f32_e32 v85, 0xbfb8aa3b, v41
	v_exp_f32_e32 v84, v84
	v_exp_f32_e32 v85, v85
	v_add_f32_e32 v38, 1.0, v38
	v_add_f32_e32 v39, 1.0, v39
	v_add_f32_e32 v84, 1.0, v84
	v_add_f32_e32 v85, 1.0, v85
	v_rcp_f32_e32 v38, v38
	v_rcp_f32_e32 v84, v84
	v_rcp_f32_e32 v85, v85
	v_rcp_f32_e32 v39, v39
	v_pk_mul_f32 v[40:41], v[72:73], v[40:41]
	v_pk_mul_f32 v[38:39], v[70:71], v[38:39]
	v_pk_mul_f32 v[40:41], v[40:41], v[84:85]
	v_pk_fma_f32 v[70:71], v[44:45], v[122:123], v[74:75]
	v_fmac_f32_dpp v70, v44, v114 row_shr:1 row_mask:0xf bank_mask:0xf
	s_nop 0
	v_fmac_f32_dpp v70, v44, v98 row_shr:2 row_mask:0xf bank_mask:0xf
	s_nop 0
	v_fmac_f32_dpp v70, v128, v114 row_shl:15 row_mask:0xf bank_mask:0xf
	v_pk_fma_f32 v[74:75], v[128:129], v[122:123], v[74:75]
	v_fmac_f32_dpp v70, v128, v98 row_shl:14 row_mask:0xf bank_mask:0xf
	v_fmac_f32_dpp v71, v45, v115 row_shr:1 row_mask:0xf bank_mask:0xf
	s_nop 0
	v_fmac_f32_dpp v71, v45, v99 row_shr:2 row_mask:0xf bank_mask:0xf
	v_pk_fma_f32 v[44:45], v[42:43], v[124:125], v[76:77]
	v_fmac_f32_dpp v71, v129, v115 row_shl:15 row_mask:0xf bank_mask:0xf
	v_pk_fma_f32 v[76:77], v[126:127], v[124:125], v[76:77]
	v_fmac_f32_dpp v71, v129, v99 row_shl:14 row_mask:0xf bank_mask:0xf
	v_fmac_f32_dpp v44, v42, v116 row_shr:1 row_mask:0xf bank_mask:0xf
	s_nop 0
	v_fmac_f32_dpp v44, v42, v100 row_shr:2 row_mask:0xf bank_mask:0xf
	v_mul_f32_e32 v42, 0xbfb8aa3b, v70
	v_fmac_f32_dpp v44, v126, v116 row_shl:15 row_mask:0xf bank_mask:0xf
	v_exp_f32_e32 v42, v42
	v_fmac_f32_dpp v44, v126, v100 row_shl:14 row_mask:0xf bank_mask:0xf
	v_fmac_f32_dpp v45, v43, v117 row_shr:1 row_mask:0xf bank_mask:0xf
	v_pk_mul_f32 v[66:67], v[66:67], v[70:71]
	v_fmac_f32_dpp v45, v43, v101 row_shr:2 row_mask:0xf bank_mask:0xf
	v_mul_f32_e32 v43, 0xbfb8aa3b, v71
	v_fmac_f32_dpp v45, v127, v117 row_shl:15 row_mask:0xf bank_mask:0xf
	v_mul_f32_e32 v72, 0xbfb8aa3b, v44
	v_fmac_f32_dpp v45, v127, v101 row_shl:14 row_mask:0xf bank_mask:0xf
	v_exp_f32_e32 v43, v43
	v_mul_f32_e32 v73, 0xbfb8aa3b, v45
	v_exp_f32_e32 v72, v72
	v_exp_f32_e32 v73, v73
	v_add_f32_e32 v42, 1.0, v42
	v_add_f32_e32 v43, 1.0, v43
	v_add_f32_e32 v72, 1.0, v72
	v_add_f32_e32 v73, 1.0, v73
	v_rcp_f32_e32 v42, v42
	v_rcp_f32_e32 v72, v72
	v_rcp_f32_e32 v73, v73
	v_rcp_f32_e32 v43, v43
	v_pk_mul_f32 v[44:45], v[68:69], v[44:45]
	v_pk_mul_f32 v[42:43], v[66:67], v[42:43]
	v_pk_mul_f32 v[44:45], v[44:45], v[72:73]
	s_nop 0
	v_fmac_f32_dpp v74, v128, v114 row_shr:1 row_mask:0xf bank_mask:0xf
	s_nop 0
	v_fmac_f32_dpp v74, v128, v98 row_shr:2 row_mask:0xf bank_mask:0xf
	s_nop 0
	v_fmac_f32_dpp v74, v118, v114 row_shl:15 row_mask:0xf bank_mask:0xf
	s_nop 0
	v_fmac_f32_dpp v74, v118, v98 row_shl:14 row_mask:0xf bank_mask:0xf
	v_fmac_f32_dpp v75, v129, v115 row_shr:1 row_mask:0xf bank_mask:0xf
	s_nop 0
	v_fmac_f32_dpp v75, v129, v99 row_shr:2 row_mask:0xf bank_mask:0xf
	s_nop 0
	v_fmac_f32_dpp v75, v119, v115 row_shl:15 row_mask:0xf bank_mask:0xf
	s_nop 0
	v_fmac_f32_dpp v75, v119, v99 row_shl:14 row_mask:0xf bank_mask:0xf
	v_fmac_f32_dpp v76, v126, v116 row_shr:1 row_mask:0xf bank_mask:0xf
	s_nop 0
	v_fmac_f32_dpp v76, v126, v100 row_shr:2 row_mask:0xf bank_mask:0xf
	s_nop 0
	v_fmac_f32_dpp v76, v120, v116 row_shl:15 row_mask:0xf bank_mask:0xf
	s_nop 0
	v_fmac_f32_dpp v76, v120, v100 row_shl:14 row_mask:0xf bank_mask:0xf
	v_fmac_f32_dpp v77, v127, v117 row_shr:1 row_mask:0xf bank_mask:0xf
	s_nop 0
	v_fmac_f32_dpp v77, v127, v101 row_shr:2 row_mask:0xf bank_mask:0xf
	s_nop 0
	v_fmac_f32_dpp v77, v121, v117 row_shl:15 row_mask:0xf bank_mask:0xf
	s_nop 0
	v_fmac_f32_dpp v77, v121, v101 row_shl:14 row_mask:0xf bank_mask:0xf
	s_and_saveexec_b64 s[52:53], s[38:39]
	s_cbranch_execz .LBB0_1343
	global_store_dwordx4 v[166:167], v[74:77], off offset:16
.LBB0_1343:
	s_or_b64 exec, exec, s[52:53]
	v_mul_f32_e32 v66, 0xbfb8aa3b, v74
	v_mul_f32_e32 v67, 0xbfb8aa3b, v75
	v_mul_f32_e32 v68, 0xbfb8aa3b, v76
	v_mul_f32_e32 v69, 0xbfb8aa3b, v77
	v_exp_f32_e32 v66, v66
	v_exp_f32_e32 v67, v67
	v_exp_f32_e32 v68, v68
	v_exp_f32_e32 v69, v69
	v_add_f32_e32 v66, 1.0, v66
	v_add_f32_e32 v67, 1.0, v67
	v_add_f32_e32 v68, 1.0, v68
	v_add_f32_e32 v69, 1.0, v69
	v_rcp_f32_e32 v66, v66
	v_rcp_f32_e32 v68, v68
	v_rcp_f32_e32 v69, v69
	v_rcp_f32_e32 v67, v67
	v_pk_mul_f32 v[70:71], v[108:109], v[76:77]
	v_pk_mul_f32 v[72:73], v[106:107], v[74:75]
	v_pk_mul_f32 v[68:69], v[70:71], v[68:69]
	v_pk_mul_f32 v[66:67], v[72:73], v[66:67]
	v_mov_b32_e32 v74, 0
	ds_read_b128 v[98:101], v223 offset:528
	ds_read_b128 v[106:109], v223 offset:1552
	ds_read_b128 v[114:117], v223 offset:2576
	ds_read_b128 v[70:73], v223 offset:3600
	v_mov_b32_e32 v110, 0
	v_mov_b32_e32 v111, 0
	v_mov_b32_e32 v112, 0
	v_mov_b32_e32 v113, 0
	s_and_saveexec_b64 s[52:53], s[0:1]
	v_add_u32_e32 v75, s77, v218
	ds_read_b128 v[110:113], v75 offset:512
	s_or_b64 exec, exec, s[52:53]
	s_waitcnt lgkmcnt(0)
	v_pk_fma_f32 v[82:83], v[58:59], v[114:115], v[70:71]
	s_nop 4
	v_fmac_f32_dpp v82, v58, v106 row_shr:1 row_mask:0xf bank_mask:0xf
	v_pk_fma_f32 v[14:15], v[14:15], v[160:161], v[54:55]
	v_fmac_f32_dpp v82, v58, v98 row_shr:2 row_mask:0xf bank_mask:0xf
	s_nop 0
	v_fmac_f32_dpp v82, v14, v106 row_shl:15 row_mask:0xf bank_mask:0xf
	v_pk_fma_f32 v[84:85], v[60:61], v[116:117], v[72:73]
	v_fmac_f32_dpp v82, v14, v98 row_shl:14 row_mask:0xf bank_mask:0xf
	v_fmac_f32_dpp v83, v59, v107 row_shr:1 row_mask:0xf bank_mask:0xf
	v_mov_b32_e32 v122, v160
	v_fmac_f32_dpp v83, v59, v99 row_shr:2 row_mask:0xf bank_mask:0xf
	v_mov_b32_e32 v123, v160
	v_fmac_f32_dpp v83, v15, v107 row_shl:15 row_mask:0xf bank_mask:0xf
	v_pk_fma_f32 v[16:17], v[16:17], v[122:123], v[56:57]
	v_fmac_f32_dpp v83, v15, v99 row_shl:14 row_mask:0xf bank_mask:0xf
	v_fmac_f32_dpp v84, v60, v108 row_shr:1 row_mask:0xf bank_mask:0xf
	s_nop 0
	v_fmac_f32_dpp v84, v60, v100 row_shr:2 row_mask:0xf bank_mask:0xf
	v_pk_fma_f32 v[124:125], v[18:19], v[162:163], v[54:55]
	v_fmac_f32_dpp v84, v16, v108 row_shl:15 row_mask:0xf bank_mask:0xf
	v_pk_fma_f32 v[18:19], v[14:15], v[114:115], v[70:71]
	v_fmac_f32_dpp v84, v16, v100 row_shl:14 row_mask:0xf bank_mask:0xf
	v_fmac_f32_dpp v85, v61, v109 row_shr:1 row_mask:0xf bank_mask:0xf
	s_nop 0
	v_fmac_f32_dpp v85, v61, v101 row_shr:2 row_mask:0xf bank_mask:0xf
	v_mov_b32_e32 v120, v162
	v_fmac_f32_dpp v85, v17, v109 row_shl:15 row_mask:0xf bank_mask:0xf
	v_mov_b32_e32 v121, v162
	v_fmac_f32_dpp v85, v17, v101 row_shl:14 row_mask:0xf bank_mask:0xf
	v_pk_fma_f32 v[76:77], v[20:21], v[120:121], v[56:57]
	v_fmac_f32_dpp v18, v14, v106 row_shr:1 row_mask:0xf bank_mask:0xf
	v_pk_fma_f32 v[20:21], v[16:17], v[116:117], v[72:73]
	v_fmac_f32_dpp v18, v14, v98 row_shr:2 row_mask:0xf bank_mask:0xf
	s_nop 0
	v_fmac_f32_dpp v18, v124, v106 row_shl:15 row_mask:0xf bank_mask:0xf
	s_nop 0
	v_fmac_f32_dpp v18, v124, v98 row_shl:14 row_mask:0xf bank_mask:0xf
	v_fmac_f32_dpp v19, v15, v107 row_shr:1 row_mask:0xf bank_mask:0xf
	v_pk_fma_f32 v[22:23], v[22:23], v[158:159], v[54:55]
	v_fmac_f32_dpp v19, v15, v99 row_shr:2 row_mask:0xf bank_mask:0xf
	v_pk_fma_f32 v[14:15], v[124:125], v[114:115], v[70:71]
	v_fmac_f32_dpp v19, v125, v107 row_shl:15 row_mask:0xf bank_mask:0xf
	v_mov_b32_e32 v118, v158
	v_fmac_f32_dpp v19, v125, v99 row_shl:14 row_mask:0xf bank_mask:0xf
	v_fmac_f32_dpp v20, v16, v108 row_shr:1 row_mask:0xf bank_mask:0xf
	v_mov_b32_e32 v119, v158
	v_fmac_f32_dpp v20, v16, v100 row_shr:2 row_mask:0xf bank_mask:0xf
	s_nop 0
	v_fmac_f32_dpp v20, v76, v108 row_shl:15 row_mask:0xf bank_mask:0xf
	v_pk_fma_f32 v[24:25], v[24:25], v[118:119], v[56:57]
	v_fmac_f32_dpp v20, v76, v100 row_shl:14 row_mask:0xf bank_mask:0xf
	v_fmac_f32_dpp v21, v17, v109 row_shr:1 row_mask:0xf bank_mask:0xf
	v_pk_fma_f32 v[70:71], v[22:23], v[114:115], v[70:71]
	v_fmac_f32_dpp v21, v17, v101 row_shr:2 row_mask:0xf bank_mask:0xf
	v_pk_fma_f32 v[16:17], v[76:77], v[116:117], v[72:73]
	v_fmac_f32_dpp v21, v77, v109 row_shl:15 row_mask:0xf bank_mask:0xf
	s_nop 0
	v_fmac_f32_dpp v21, v77, v101 row_shl:14 row_mask:0xf bank_mask:0xf
	v_pk_fma_f32 v[72:73], v[24:25], v[116:117], v[72:73]
	v_fmac_f32_dpp v14, v124, v106 row_shr:1 row_mask:0xf bank_mask:0xf
	s_nop 0
	v_fmac_f32_dpp v14, v124, v98 row_shr:2 row_mask:0xf bank_mask:0xf
	v_mov_b32_e32 v75, 0
	v_fmac_f32_dpp v14, v22, v106 row_shl:15 row_mask:0xf bank_mask:0xf
	s_nop 0
	v_fmac_f32_dpp v14, v22, v98 row_shl:14 row_mask:0xf bank_mask:0xf
	v_fmac_f32_dpp v15, v125, v107 row_shr:1 row_mask:0xf bank_mask:0xf
	s_nop 0
	v_fmac_f32_dpp v15, v125, v99 row_shr:2 row_mask:0xf bank_mask:0xf
	s_nop 0
	v_fmac_f32_dpp v15, v23, v107 row_shl:15 row_mask:0xf bank_mask:0xf
	s_nop 0
	v_fmac_f32_dpp v15, v23, v99 row_shl:14 row_mask:0xf bank_mask:0xf
	v_fmac_f32_dpp v16, v76, v108 row_shr:1 row_mask:0xf bank_mask:0xf
	s_nop 0
	v_fmac_f32_dpp v16, v76, v100 row_shr:2 row_mask:0xf bank_mask:0xf
	v_mov_b32_e32 v76, 0
	v_fmac_f32_dpp v16, v24, v108 row_shl:15 row_mask:0xf bank_mask:0xf
	s_nop 0
	v_fmac_f32_dpp v16, v24, v100 row_shl:14 row_mask:0xf bank_mask:0xf
	v_fmac_f32_dpp v17, v77, v109 row_shr:1 row_mask:0xf bank_mask:0xf
	s_nop 0
	v_fmac_f32_dpp v17, v77, v101 row_shr:2 row_mask:0xf bank_mask:0xf
	v_mov_b32_e32 v77, 0
	v_fmac_f32_dpp v17, v25, v109 row_shl:15 row_mask:0xf bank_mask:0xf
	s_nop 0
	v_fmac_f32_dpp v17, v25, v101 row_shl:14 row_mask:0xf bank_mask:0xf
	s_nop 0
	v_fmac_f32_dpp v70, v22, v106 row_shr:1 row_mask:0xf bank_mask:0xf
	s_nop 0
	v_fmac_f32_dpp v70, v22, v98 row_shr:2 row_mask:0xf bank_mask:0xf
	s_nop 0
	v_fmac_f32_dpp v70, v110, v106 row_shl:15 row_mask:0xf bank_mask:0xf
	s_nop 0
	v_fmac_f32_dpp v70, v110, v98 row_shl:14 row_mask:0xf bank_mask:0xf
	v_fmac_f32_dpp v71, v23, v107 row_shr:1 row_mask:0xf bank_mask:0xf
	s_nop 0
	v_fmac_f32_dpp v71, v23, v99 row_shr:2 row_mask:0xf bank_mask:0xf
	s_nop 0
	v_fmac_f32_dpp v71, v111, v107 row_shl:15 row_mask:0xf bank_mask:0xf
	s_nop 0
	v_fmac_f32_dpp v71, v111, v99 row_shl:14 row_mask:0xf bank_mask:0xf
	v_fmac_f32_dpp v72, v24, v108 row_shr:1 row_mask:0xf bank_mask:0xf
	s_nop 0
	v_fmac_f32_dpp v72, v24, v100 row_shr:2 row_mask:0xf bank_mask:0xf
	s_nop 0
	v_fmac_f32_dpp v72, v112, v108 row_shl:15 row_mask:0xf bank_mask:0xf
	s_nop 0
	v_fmac_f32_dpp v72, v112, v100 row_shl:14 row_mask:0xf bank_mask:0xf
	v_fmac_f32_dpp v73, v25, v109 row_shr:1 row_mask:0xf bank_mask:0xf
	s_nop 0
	v_fmac_f32_dpp v73, v25, v101 row_shr:2 row_mask:0xf bank_mask:0xf
	s_nop 0
	v_fmac_f32_dpp v73, v113, v109 row_shl:15 row_mask:0xf bank_mask:0xf
	s_nop 0
	v_fmac_f32_dpp v73, v113, v101 row_shl:14 row_mask:0xf bank_mask:0xf
	s_nop 0
	ds_read_b128 v[54:57], v223 offset:16
	ds_read_b128 v[58:61], v223 offset:1040
	ds_read_b128 v[98:101], v223 offset:2064
	ds_read_b128 v[22:25], v223 offset:3088
	s_and_saveexec_b64 s[52:53], s[0:1]
	v_add_u32_e32 v74, 0, v218
	v_add_u32_e32 v74, 0x20000, v74
	ds_read_b128 v[74:77], v74
	s_or_b64 exec, exec, s[52:53]
	v_pk_fma_f32 v[106:107], v[8:9], v[120:121], v[32:33]
	v_pk_fma_f32 v[8:9], v[2:3], v[160:161], v[30:31]
	s_waitcnt lgkmcnt(0)
	v_pk_fma_f32 v[2:3], v[26:27], v[98:99], v[22:23]
	s_nop 4
	v_fmac_f32_dpp v2, v26, v58 row_shr:1 row_mask:0xf bank_mask:0xf
	s_nop 0
	v_fmac_f32_dpp v2, v26, v54 row_shr:2 row_mask:0xf bank_mask:0xf
	v_pk_fma_f32 v[108:109], v[6:7], v[162:163], v[30:31]
	v_fmac_f32_dpp v2, v8, v58 row_shl:15 row_mask:0xf bank_mask:0xf
	v_pk_fma_f32 v[6:7], v[4:5], v[122:123], v[32:33]
	v_fmac_f32_dpp v2, v8, v54 row_shl:14 row_mask:0xf bank_mask:0xf
	v_fmac_f32_dpp v3, v27, v59 row_shr:1 row_mask:0xf bank_mask:0xf
	v_pk_fma_f32 v[4:5], v[28:29], v[100:101], v[24:25]
	v_fmac_f32_dpp v3, v27, v55 row_shr:2 row_mask:0xf bank_mask:0xf
	s_nop 0
	v_fmac_f32_dpp v3, v9, v59 row_shl:15 row_mask:0xf bank_mask:0xf
	v_mul_f32_e32 v26, 0xbfb8aa3b, v2
	v_fmac_f32_dpp v3, v9, v55 row_shl:14 row_mask:0xf bank_mask:0xf
	v_fmac_f32_dpp v4, v28, v60 row_shr:1 row_mask:0xf bank_mask:0xf
	v_exp_f32_e32 v26, v26
	v_fmac_f32_dpp v4, v28, v56 row_shr:2 row_mask:0xf bank_mask:0xf
	v_mul_f32_e32 v27, 0xbfb8aa3b, v3
	v_fmac_f32_dpp v4, v6, v60 row_shl:15 row_mask:0xf bank_mask:0xf
	v_exp_f32_e32 v27, v27
	v_fmac_f32_dpp v4, v6, v56 row_shl:14 row_mask:0xf bank_mask:0xf
	v_fmac_f32_dpp v5, v29, v61 row_shr:1 row_mask:0xf bank_mask:0xf
	v_add_f32_e32 v26, 1.0, v26
	v_fmac_f32_dpp v5, v29, v57 row_shr:2 row_mask:0xf bank_mask:0xf
	v_mul_f32_e32 v28, 0xbfb8aa3b, v4
	v_fmac_f32_dpp v5, v7, v61 row_shl:15 row_mask:0xf bank_mask:0xf
	v_exp_f32_e32 v28, v28
	v_fmac_f32_dpp v5, v7, v57 row_shl:14 row_mask:0xf bank_mask:0xf
	v_add_f32_e32 v27, 1.0, v27
	v_mul_f32_e32 v29, 0xbfb8aa3b, v5
	v_exp_f32_e32 v29, v29
	v_add_f32_e32 v28, 1.0, v28
	v_rcp_f32_e32 v26, v26
	v_rcp_f32_e32 v28, v28
	v_add_f32_e32 v29, 1.0, v29
	v_rcp_f32_e32 v29, v29
	v_rcp_f32_e32 v27, v27
	v_pk_mul_f32 v[4:5], v[84:85], v[4:5]
	v_pk_mul_f32 v[2:3], v[82:83], v[2:3]
	v_pk_mul_f32 v[4:5], v[4:5], v[28:29]
	v_pk_mul_f32 v[2:3], v[2:3], v[26:27]
	v_pk_fma_f32 v[26:27], v[8:9], v[98:99], v[22:23]
	v_fmac_f32_dpp v26, v8, v58 row_shr:1 row_mask:0xf bank_mask:0xf
	s_nop 0
	v_fmac_f32_dpp v26, v8, v54 row_shr:2 row_mask:0xf bank_mask:0xf
	s_nop 0
	v_fmac_f32_dpp v26, v108, v58 row_shl:15 row_mask:0xf bank_mask:0xf
	v_pk_fma_f32 v[10:11], v[10:11], v[158:159], v[30:31]
	v_fmac_f32_dpp v26, v108, v54 row_shl:14 row_mask:0xf bank_mask:0xf
	v_fmac_f32_dpp v27, v9, v59 row_shr:1 row_mask:0xf bank_mask:0xf
	v_pk_fma_f32 v[12:13], v[12:13], v[118:119], v[32:33]
	v_fmac_f32_dpp v27, v9, v55 row_shr:2 row_mask:0xf bank_mask:0xf
	v_pk_fma_f32 v[8:9], v[6:7], v[100:101], v[24:25]
	v_fmac_f32_dpp v27, v109, v59 row_shl:15 row_mask:0xf bank_mask:0xf
	s_ashr_i32 s51, s50, 31
	v_fmac_f32_dpp v27, v109, v55 row_shl:14 row_mask:0xf bank_mask:0xf
	v_fmac_f32_dpp v8, v6, v60 row_shr:1 row_mask:0xf bank_mask:0xf
	s_andn2_b64 vcc, exec, s[4:5]
	v_fmac_f32_dpp v8, v6, v56 row_shr:2 row_mask:0xf bank_mask:0xf
	v_mul_f32_e32 v6, 0xbfb8aa3b, v26
	v_fmac_f32_dpp v8, v106, v60 row_shl:15 row_mask:0xf bank_mask:0xf
	v_exp_f32_e32 v6, v6
	v_fmac_f32_dpp v8, v106, v56 row_shl:14 row_mask:0xf bank_mask:0xf
	v_fmac_f32_dpp v9, v7, v61 row_shr:1 row_mask:0xf bank_mask:0xf
	v_pk_mul_f32 v[18:19], v[18:19], v[26:27]
	v_fmac_f32_dpp v9, v7, v57 row_shr:2 row_mask:0xf bank_mask:0xf
	v_mul_f32_e32 v7, 0xbfb8aa3b, v27
	v_fmac_f32_dpp v9, v107, v61 row_shl:15 row_mask:0xf bank_mask:0xf
	v_mul_f32_e32 v28, 0xbfb8aa3b, v8
	v_fmac_f32_dpp v9, v107, v57 row_shl:14 row_mask:0xf bank_mask:0xf
	v_exp_f32_e32 v7, v7
	v_mul_f32_e32 v29, 0xbfb8aa3b, v9
	v_exp_f32_e32 v28, v28
	v_exp_f32_e32 v29, v29
	v_add_f32_e32 v6, 1.0, v6
	v_add_f32_e32 v7, 1.0, v7
	v_add_f32_e32 v28, 1.0, v28
	v_add_f32_e32 v29, 1.0, v29
	v_rcp_f32_e32 v6, v6
	v_rcp_f32_e32 v28, v28
	v_rcp_f32_e32 v29, v29
	v_rcp_f32_e32 v7, v7
	v_pk_mul_f32 v[8:9], v[20:21], v[8:9]
	v_pk_fma_f32 v[20:21], v[106:107], v[100:101], v[24:25]
	v_pk_mul_f32 v[8:9], v[8:9], v[28:29]
	v_pk_mul_f32 v[6:7], v[18:19], v[6:7]
	v_pk_fma_f32 v[18:19], v[108:109], v[98:99], v[22:23]
	v_fmac_f32_dpp v18, v108, v58 row_shr:1 row_mask:0xf bank_mask:0xf
	s_nop 0
	v_fmac_f32_dpp v18, v108, v54 row_shr:2 row_mask:0xf bank_mask:0xf
	s_nop 0
	v_fmac_f32_dpp v18, v10, v58 row_shl:15 row_mask:0xf bank_mask:0xf
	v_pk_fma_f32 v[24:25], v[12:13], v[100:101], v[24:25]
	v_fmac_f32_dpp v18, v10, v54 row_shl:14 row_mask:0xf bank_mask:0xf
	v_fmac_f32_dpp v19, v109, v59 row_shr:1 row_mask:0xf bank_mask:0xf
	s_nop 0
	v_fmac_f32_dpp v19, v109, v55 row_shr:2 row_mask:0xf bank_mask:0xf
	v_mul_f32_e32 v26, 0xbfb8aa3b, v18
	v_fmac_f32_dpp v19, v11, v59 row_shl:15 row_mask:0xf bank_mask:0xf
	v_exp_f32_e32 v26, v26
	v_fmac_f32_dpp v19, v11, v55 row_shl:14 row_mask:0xf bank_mask:0xf
	v_fmac_f32_dpp v20, v106, v60 row_shr:1 row_mask:0xf bank_mask:0xf
	s_mov_b64 s[4:5], -1
	v_fmac_f32_dpp v20, v106, v56 row_shr:2 row_mask:0xf bank_mask:0xf
	v_mul_f32_e32 v27, 0xbfb8aa3b, v19
	v_fmac_f32_dpp v20, v12, v60 row_shl:15 row_mask:0xf bank_mask:0xf
	v_exp_f32_e32 v27, v27
	v_fmac_f32_dpp v20, v12, v56 row_shl:14 row_mask:0xf bank_mask:0xf
	v_fmac_f32_dpp v21, v107, v61 row_shr:1 row_mask:0xf bank_mask:0xf
	v_add_f32_e32 v26, 1.0, v26
	v_fmac_f32_dpp v21, v107, v57 row_shr:2 row_mask:0xf bank_mask:0xf
	v_mul_f32_e32 v28, 0xbfb8aa3b, v20
	v_fmac_f32_dpp v21, v13, v61 row_shl:15 row_mask:0xf bank_mask:0xf
	v_exp_f32_e32 v28, v28
	v_fmac_f32_dpp v21, v13, v57 row_shl:14 row_mask:0xf bank_mask:0xf
	v_add_f32_e32 v27, 1.0, v27
	v_mul_f32_e32 v29, 0xbfb8aa3b, v21
	v_exp_f32_e32 v29, v29
	v_add_f32_e32 v28, 1.0, v28
	v_rcp_f32_e32 v26, v26
	v_rcp_f32_e32 v28, v28
	v_add_f32_e32 v29, 1.0, v29
	v_rcp_f32_e32 v29, v29
	v_rcp_f32_e32 v27, v27
	v_pk_mul_f32 v[16:17], v[16:17], v[20:21]
	v_pk_mul_f32 v[14:15], v[14:15], v[18:19]
	v_pk_mul_f32 v[16:17], v[16:17], v[28:29]
	v_pk_mul_f32 v[14:15], v[14:15], v[26:27]
	v_pk_fma_f32 v[18:19], v[10:11], v[98:99], v[22:23]
	v_fmac_f32_dpp v18, v10, v58 row_shr:1 row_mask:0xf bank_mask:0xf
	s_nop 0
	v_fmac_f32_dpp v18, v10, v54 row_shr:2 row_mask:0xf bank_mask:0xf
	v_lshl_add_u32 v26, s30, 8, v173
	v_fmac_f32_dpp v18, v74, v58 row_shl:15 row_mask:0xf bank_mask:0xf
	v_mov_b64_e32 v[22:23], s[66:67]
	v_fmac_f32_dpp v18, v74, v54 row_shl:14 row_mask:0xf bank_mask:0xf
	v_fmac_f32_dpp v19, v11, v59 row_shr:1 row_mask:0xf bank_mask:0xf
	s_nop 0
	v_fmac_f32_dpp v19, v11, v55 row_shr:2 row_mask:0xf bank_mask:0xf
	v_mul_f32_e32 v10, 0xbfb8aa3b, v18
	v_fmac_f32_dpp v19, v75, v59 row_shl:15 row_mask:0xf bank_mask:0xf
	v_exp_f32_e32 v10, v10
	v_fmac_f32_dpp v19, v75, v55 row_shl:14 row_mask:0xf bank_mask:0xf
	v_fmac_f32_dpp v24, v12, v60 row_shr:1 row_mask:0xf bank_mask:0xf
	s_nop 0
	v_fmac_f32_dpp v24, v12, v56 row_shr:2 row_mask:0xf bank_mask:0xf
	v_mul_f32_e32 v11, 0xbfb8aa3b, v19
	v_fmac_f32_dpp v24, v76, v60 row_shl:15 row_mask:0xf bank_mask:0xf
	v_exp_f32_e32 v11, v11
	v_fmac_f32_dpp v24, v76, v56 row_shl:14 row_mask:0xf bank_mask:0xf
	v_fmac_f32_dpp v25, v13, v61 row_shr:1 row_mask:0xf bank_mask:0xf
	v_add_f32_e32 v10, 1.0, v10
	v_fmac_f32_dpp v25, v13, v57 row_shr:2 row_mask:0xf bank_mask:0xf
	v_mul_f32_e32 v12, 0xbfb8aa3b, v24
	v_fmac_f32_dpp v25, v77, v61 row_shl:15 row_mask:0xf bank_mask:0xf
	v_exp_f32_e32 v12, v12
	v_fmac_f32_dpp v25, v77, v57 row_shl:14 row_mask:0xf bank_mask:0xf
	v_add_f32_e32 v11, 1.0, v11
	v_mul_f32_e32 v13, 0xbfb8aa3b, v25
	v_exp_f32_e32 v13, v13
	v_add_f32_e32 v12, 1.0, v12
	v_rcp_f32_e32 v10, v10
	v_rcp_f32_e32 v12, v12
	v_add_f32_e32 v13, 1.0, v13
	v_rcp_f32_e32 v13, v13
	v_rcp_f32_e32 v11, v11
	v_pk_mul_f32 v[20:21], v[72:73], v[24:25]
	v_mad_i64_i32 v[24:25], s[30:31], v26, s81, v[22:23]
	s_lshl_b64 s[30:31], s[50:51], 1
	v_pk_mul_f32 v[18:19], v[70:71], v[18:19]
	v_lshl_add_u64 v[24:25], v[24:25], 0, s[30:31]
	v_pk_mul_f32 v[12:13], v[20:21], v[12:13]
	v_pk_mul_f32 v[10:11], v[18:19], v[10:11]
	v_lshl_add_u64 v[24:25], v[24:25], 0, v[184:185]
	v_cvt_pk_bf16_f32 v18, v78, v79
	v_cvt_pk_bf16_f32 v19, v80, v81
	v_cvt_pk_bf16_f32 v20, v66, v67
	v_cvt_pk_bf16_f32 v21, v68, v69
	global_store_dwordx4 v[24:25], v[18:21], off
	v_or_b32_e32 v24, 16, v26
	v_mad_i64_i32 v[24:25], s[50:51], v24, s81, v[22:23]
	v_lshl_add_u64 v[24:25], v[24:25], 0, s[30:31]
	v_lshl_add_u64 v[24:25], v[24:25], 0, v[184:185]
	v_cvt_pk_bf16_f32 v18, v62, v63
	v_cvt_pk_bf16_f32 v19, v64, v65
	v_cvt_pk_bf16_f32 v20, v42, v43
	v_cvt_pk_bf16_f32 v21, v44, v45
	global_store_dwordx4 v[24:25], v[18:21], off
	v_or_b32_e32 v24, 32, v26
	v_mad_i64_i32 v[24:25], s[50:51], v24, s81, v[22:23]
	v_lshl_add_u64 v[24:25], v[24:25], 0, s[30:31]
	v_lshl_add_u64 v[24:25], v[24:25], 0, v[184:185]
	v_cvt_pk_bf16_f32 v18, v50, v51
	v_cvt_pk_bf16_f32 v19, v52, v53
	v_cvt_pk_bf16_f32 v20, v38, v39
	v_cvt_pk_bf16_f32 v21, v40, v41
	global_store_dwordx4 v[24:25], v[18:21], off
	v_or_b32_e32 v24, 48, v26
	v_mad_i64_i32 v[24:25], s[50:51], v24, s81, v[22:23]
	v_lshl_add_u64 v[24:25], v[24:25], 0, s[30:31]
	v_lshl_add_u64 v[24:25], v[24:25], 0, v[184:185]
	v_cvt_pk_bf16_f32 v18, v46, v47
	v_cvt_pk_bf16_f32 v19, v48, v49
	v_cvt_pk_bf16_f32 v20, v34, v35
	v_cvt_pk_bf16_f32 v21, v36, v37
	global_store_dwordx4 v[24:25], v[18:21], off
	v_add_u32_e32 v24, 0x80, v26
	s_nop 0
	v_cvt_pk_bf16_f32 v18, v102, v103
	v_cvt_pk_bf16_f32 v19, v104, v105
	v_cvt_pk_bf16_f32 v20, v10, v11
	v_mad_i64_i32 v[10:11], s[50:51], v24, s81, v[22:23]
	v_lshl_add_u64 v[10:11], v[10:11], 0, s[30:31]
	v_lshl_add_u64 v[10:11], v[10:11], 0, v[184:185]
	v_cvt_pk_bf16_f32 v21, v12, v13
	global_store_dwordx4 v[10:11], v[18:21], off
	v_cvt_pk_bf16_f32 v10, v94, v95
	v_cvt_pk_bf16_f32 v11, v96, v97
	v_cvt_pk_bf16_f32 v12, v14, v15
	v_add_u32_e32 v14, 0x90, v26
	v_mad_i64_i32 v[14:15], s[50:51], v14, s81, v[22:23]
	v_lshl_add_u64 v[14:15], v[14:15], 0, s[30:31]
	v_lshl_add_u64 v[14:15], v[14:15], 0, v[184:185]
	v_cvt_pk_bf16_f32 v13, v16, v17
	global_store_dwordx4 v[14:15], v[10:13], off
	s_nop 1
	v_cvt_pk_bf16_f32 v10, v90, v91
	v_cvt_pk_bf16_f32 v11, v92, v93
	v_cvt_pk_bf16_f32 v12, v6, v7
	v_add_u32_e32 v6, 0xa0, v26
	v_mad_i64_i32 v[6:7], s[50:51], v6, s81, v[22:23]
	v_lshl_add_u64 v[6:7], v[6:7], 0, s[30:31]
	v_lshl_add_u64 v[6:7], v[6:7], 0, v[184:185]
	v_cvt_pk_bf16_f32 v13, v8, v9
	global_store_dwordx4 v[6:7], v[10:13], off
	v_cvt_pk_bf16_f32 v6, v86, v87
	v_cvt_pk_bf16_f32 v7, v88, v89
	v_cvt_pk_bf16_f32 v8, v2, v3
	v_add_u32_e32 v2, 0xb0, v26
	v_mad_i64_i32 v[2:3], s[50:51], v2, s81, v[22:23]
	v_lshl_add_u64 v[2:3], v[2:3], 0, s[30:31]
	v_lshl_add_u64 v[2:3], v[2:3], 0, v[184:185]
	v_cvt_pk_bf16_f32 v9, v4, v5
	global_store_dwordx4 v[2:3], v[6:9], off
	s_cbranch_vccnz .LBB0_1313
	s_andn2_b64 vcc, exec, s[20:21]
	s_mov_b32 s43, s44
	s_mov_b64 s[30:31], s[16:17]
	s_mov_b64 s[4:5], s[40:41]
	s_cbranch_vccnz .LBB0_1350
	s_ashr_i32 s4, s44, 5
	s_mul_hi_i32 s5, s4, 0x5800
	s_mulk_i32 s4, 0x5800
	s_add_u32 s30, s3, s4
	s_addc_u32 s31, s6, s5
	s_mov_b32 s43, s42
	s_mov_b64 s[4:5], s[14:15]
